# GATES pair tiles: first 78 per-XCD tickets are 128x256 pairs, last 36 singles
# baseline (speedup 1.0000x reference)
.LBB0_256:
	s_or_b64 exec, exec, s[8:9]
	s_mov_b64 s[8:9], src_shared_base
	v_mov_b32_e32 v121, s9
	s_waitcnt lgkmcnt(0)
	s_barrier
	flat_load_dword v0, v[120:121] sc0 sc1
	s_waitcnt vmcnt(0)
	s_mov_b32 s63, 0
	s_mov_b32 s62, 0
	s_mov_b32 s61, 0
	s_cmp_eq_u32 s98, 0
	s_cbranch_scc1 .Lgq_skip1
	v_readfirstlane_b32 s60, v0
	s_cmp_lt_u32 s60, 78
	s_cbranch_scc0 .Lgd_s1
	s_mov_b32 s63, 1
	s_mul_hi_u32 s13, s60, 0x2aaaaaab
	s_mul_i32 s8, s13, 6
	s_sub_i32 s8, s60, s8
	s_lshl_b32 s13, s13, 1
	s_branch .Lgd_e1
.Lgd_s1:
	s_add_i32 s8, s60, 0xffffffb2
	s_cmp_lt_u32 s8, 36
	s_cbranch_scc0 .Lgd_x1
	s_mul_hi_u32 s13, s8, 0x2aaaaaab
	s_mul_i32 s9, s13, 6
	s_sub_i32 s8, s8, s9
	s_add_i32 s13, s13, 26
.Lgd_e1:
	s_mul_i32 s13, s13, 48
	s_lshl_b32 s8, s8, 3
	s_add_i32 s13, s13, s8
	s_add_i32 s13, s13, s99
	s_branch .Lgd_d1
.Lgd_x1:
	s_add_i32 s13, s60, 0x600
.Lgd_d1:
	v_mov_b32_e32 v0, s13

.LBB0_258:
	s_or_b64 exec, exec, s[16:17]
	s_cmp_eq_u32 s62, 1
	s_cbranch_scc0 .Lgt_ein
	v_mov_b32_e32 v202, v92
	v_mov_b32_e32 v203, v93
.Lgt_ein:
	s_waitcnt vmcnt(0)
	v_cvt_f32_i32_e32 v132, v89
	v_lshrrev_b32_e32 v89, 2, v92
	ds_read_b128 v[104:107], v96
	ds_read_b128 v[108:111], v96 offset:32
	ds_read_b128 v[112:115], v96 offset:64
	ds_read_b128 v[128:131], v96 offset:96
	ds_read_b128 v[76:79], v96 offset:128
	ds_read_b128 v[72:75], v96 offset:160
	ds_read_b128 v[68:71], v96 offset:192
	ds_read_b128 v[64:67], v96 offset:224
	v_cvt_f32_i32_e32 v134, v91
	v_add_u32_e32 v89, v89, v93
	v_and_b32_e32 v91, 7, v93
	s_movk_i32 s13, 0xff8
	v_mov_b32_e32 v133, v55
	s_waitcnt lgkmcnt(0)
	v_mov_b32_e32 v119, v111
	s_and_b64 s[16:17], exec, s[40:41]
	v_and_or_b32 v89, v89, s13, v91
	v_pk_mul_f32 v[132:133], v[132:133], v[118:119]
	s_or_b64 s[14:15], s[16:17], s[14:15]
	v_lshlrev_b32_e32 v116, 15, v89
	v_fma_f32 v48, v48, v104, v132
	v_fma_f32 v49, v49, v105, v132
	v_fma_f32 v50, v50, v106, v132
	v_fma_f32 v51, v51, v107, v132
	v_fma_f32 v52, v52, v108, v132
	v_fma_f32 v53, v53, v109, v132
	v_fma_f32 v54, v54, v110, v132
	v_add_f32_e32 v55, v132, v133
	v_fma_f32 v56, v56, v112, v132
	v_fma_f32 v57, v57, v113, v132
	v_fma_f32 v58, v58, v114, v132
	v_fma_f32 v59, v59, v115, v132
	v_fma_f32 v60, v60, v128, v132
	v_fma_f32 v61, v61, v129, v132
	v_fma_f32 v62, v62, v130, v132
	v_fma_f32 v63, v63, v131, v132
	v_lshl_add_u64 v[92:93], v[86:87], 0, v[116:117]
	v_mul_f32_e32 v48, 0xbfb8aa3b, v48
	v_mul_f32_e32 v49, 0xbfb8aa3b, v49
	v_mul_f32_e32 v50, 0xbfb8aa3b, v50
	v_mul_f32_e32 v51, 0xbfb8aa3b, v51
	v_mul_f32_e32 v52, 0xbfb8aa3b, v52
	v_mul_f32_e32 v53, 0xbfb8aa3b, v53
	v_mul_f32_e32 v54, 0xbfb8aa3b, v54
	v_mul_f32_e32 v55, 0xbfb8aa3b, v55
	v_mul_f32_e32 v56, 0xbfb8aa3b, v56
	v_mul_f32_e32 v57, 0xbfb8aa3b, v57
	v_mul_f32_e32 v58, 0xbfb8aa3b, v58
	v_mul_f32_e32 v59, 0xbfb8aa3b, v59
	v_mul_f32_e32 v60, 0xbfb8aa3b, v60
	v_mul_f32_e32 v61, 0xbfb8aa3b, v61
	v_mul_f32_e32 v62, 0xbfb8aa3b, v62
	v_mul_f32_e32 v63, 0xbfb8aa3b, v63
	v_exp_f32_e32 v48, v48
	v_exp_f32_e32 v49, v49
	v_exp_f32_e32 v50, v50
	v_exp_f32_e32 v51, v51
	v_exp_f32_e32 v52, v52
	v_exp_f32_e32 v53, v53
	v_exp_f32_e32 v54, v54
	v_exp_f32_e32 v55, v55
	v_exp_f32_e32 v56, v56
	v_exp_f32_e32 v57, v57
	v_exp_f32_e32 v58, v58
	v_exp_f32_e32 v59, v59
	v_exp_f32_e32 v60, v60
	v_exp_f32_e32 v61, v61
	v_exp_f32_e32 v62, v62
	v_exp_f32_e32 v63, v63
	v_add_f32_e32 v48, 1.0, v48
	v_add_f32_e32 v49, 1.0, v49
	v_add_f32_e32 v50, 1.0, v50
	v_add_f32_e32 v51, 1.0, v51
	v_add_f32_e32 v52, 1.0, v52
	v_add_f32_e32 v53, 1.0, v53
	v_add_f32_e32 v54, 1.0, v54
	v_add_f32_e32 v55, 1.0, v55
	v_add_f32_e32 v56, 1.0, v56
	v_add_f32_e32 v57, 1.0, v57
	v_add_f32_e32 v58, 1.0, v58
	v_add_f32_e32 v59, 1.0, v59
	v_add_f32_e32 v60, 1.0, v60
	v_add_f32_e32 v61, 1.0, v61
	v_add_f32_e32 v62, 1.0, v62
	v_add_f32_e32 v63, 1.0, v63
	v_rcp_f32_e32 v48, v48
	v_rcp_f32_e32 v49, v49
	v_rcp_f32_e32 v50, v50
	v_rcp_f32_e32 v51, v51
	v_rcp_f32_e32 v52, v52
	v_rcp_f32_e32 v53, v53
	v_rcp_f32_e32 v54, v54
	v_rcp_f32_e32 v55, v55
	v_rcp_f32_e32 v56, v56
	v_rcp_f32_e32 v57, v57
	v_rcp_f32_e32 v58, v58
	v_rcp_f32_e32 v59, v59
	v_rcp_f32_e32 v60, v60
	v_rcp_f32_e32 v61, v61
	v_rcp_f32_e32 v62, v62
	v_rcp_f32_e32 v63, v63
	s_movk_i32 s13, 0x2000
	v_cvt_pk_bf16_f32 v48, v48, v49
	v_cvt_pk_bf16_f32 v49, v50, v51
	v_cvt_pk_bf16_f32 v50, v52, v53
	v_cvt_pk_bf16_f32 v51, v54, v55
	v_add_co_u32_e32 v52, vcc, s13, v92
	global_store_dwordx4 v[92:93], v[48:51], off
	s_nop 0
	v_addc_co_u32_e32 v53, vcc, 0, v93, vcc
	v_cvt_pk_bf16_f32 v48, v56, v57
	v_cvt_pk_bf16_f32 v49, v58, v59
	v_cvt_pk_bf16_f32 v50, v60, v61
	v_cvt_pk_bf16_f32 v51, v62, v63
	v_mov_b32_e32 v135, v39
	global_store_dwordx4 v[52:53], v[48:51], off offset:-4096
	s_nop 1
	v_pk_mul_f32 v[48:49], v[134:135], v[118:119]
	s_nop 0
	v_fma_f32 v32, v32, v104, v48
	v_fma_f32 v33, v33, v105, v48
	v_fma_f32 v34, v34, v106, v48
	v_fma_f32 v35, v35, v107, v48
	v_fma_f32 v36, v36, v108, v48
	v_fma_f32 v37, v37, v109, v48
	v_fma_f32 v38, v38, v110, v48
	v_add_f32_e32 v39, v48, v49
	v_fma_f32 v40, v40, v112, v48
	v_fma_f32 v41, v41, v113, v48
	v_fma_f32 v42, v42, v114, v48
	v_fma_f32 v43, v43, v115, v48
	v_fma_f32 v44, v44, v128, v48
	v_fma_f32 v45, v45, v129, v48
	v_fma_f32 v46, v46, v130, v48
	v_fma_f32 v47, v47, v131, v48
	v_mul_f32_e32 v32, 0xbfb8aa3b, v32
	v_mul_f32_e32 v33, 0xbfb8aa3b, v33
	v_mul_f32_e32 v34, 0xbfb8aa3b, v34
	v_mul_f32_e32 v35, 0xbfb8aa3b, v35
	v_mul_f32_e32 v36, 0xbfb8aa3b, v36
	v_mul_f32_e32 v37, 0xbfb8aa3b, v37
	v_mul_f32_e32 v38, 0xbfb8aa3b, v38
	v_mul_f32_e32 v39, 0xbfb8aa3b, v39
	v_mul_f32_e32 v40, 0xbfb8aa3b, v40
	v_mul_f32_e32 v41, 0xbfb8aa3b, v41
	v_mul_f32_e32 v42, 0xbfb8aa3b, v42
	v_mul_f32_e32 v43, 0xbfb8aa3b, v43
	v_mul_f32_e32 v44, 0xbfb8aa3b, v44
	v_mul_f32_e32 v45, 0xbfb8aa3b, v45
	v_mul_f32_e32 v46, 0xbfb8aa3b, v46
	v_mul_f32_e32 v47, 0xbfb8aa3b, v47
	v_exp_f32_e32 v32, v32
	v_exp_f32_e32 v33, v33
	v_exp_f32_e32 v34, v34
	v_exp_f32_e32 v35, v35
	v_exp_f32_e32 v36, v36
	v_exp_f32_e32 v37, v37
	v_exp_f32_e32 v38, v38
	v_exp_f32_e32 v39, v39
	v_exp_f32_e32 v40, v40
	v_exp_f32_e32 v41, v41
	v_exp_f32_e32 v42, v42
	v_exp_f32_e32 v43, v43
	v_exp_f32_e32 v44, v44
	v_exp_f32_e32 v45, v45
	v_exp_f32_e32 v46, v46
	v_exp_f32_e32 v47, v47
	v_add_f32_e32 v32, 1.0, v32
	v_add_f32_e32 v33, 1.0, v33
	v_add_f32_e32 v34, 1.0, v34
	v_add_f32_e32 v35, 1.0, v35
	v_add_f32_e32 v36, 1.0, v36
	v_add_f32_e32 v37, 1.0, v37
	v_add_f32_e32 v38, 1.0, v38
	v_add_f32_e32 v39, 1.0, v39
	v_add_f32_e32 v40, 1.0, v40
	v_add_f32_e32 v41, 1.0, v41
	v_add_f32_e32 v42, 1.0, v42
	v_add_f32_e32 v43, 1.0, v43
	v_add_f32_e32 v44, 1.0, v44
	v_add_f32_e32 v45, 1.0, v45
	v_add_f32_e32 v46, 1.0, v46
	v_add_f32_e32 v47, 1.0, v47
	v_rcp_f32_e32 v32, v32
	v_rcp_f32_e32 v33, v33
	v_rcp_f32_e32 v34, v34
	v_rcp_f32_e32 v35, v35
	v_rcp_f32_e32 v36, v36
	v_rcp_f32_e32 v37, v37
	v_rcp_f32_e32 v38, v38
	v_rcp_f32_e32 v39, v39
	v_rcp_f32_e32 v40, v40
	v_rcp_f32_e32 v41, v41
	v_rcp_f32_e32 v42, v42
	v_rcp_f32_e32 v43, v43
	v_rcp_f32_e32 v44, v44
	v_rcp_f32_e32 v45, v45
	v_rcp_f32_e32 v46, v46
	v_rcp_f32_e32 v47, v47
	s_movk_i32 s13, 0x4000
	v_cvt_pk_bf16_f32 v32, v32, v33
	v_cvt_pk_bf16_f32 v33, v34, v35
	v_cvt_pk_bf16_f32 v34, v36, v37
	v_cvt_pk_bf16_f32 v35, v38, v39
	v_add_co_u32_e32 v36, vcc, s13, v92
	global_store_dwordx4 v[52:53], v[32:35], off
	s_nop 0
	v_addc_co_u32_e32 v37, vcc, 0, v93, vcc
	v_cvt_pk_bf16_f32 v32, v40, v41
	v_cvt_pk_bf16_f32 v33, v42, v43
	v_cvt_pk_bf16_f32 v34, v44, v45
	v_cvt_pk_bf16_f32 v35, v46, v47
	v_fma_f32 v16, v16, v76, v132
	v_fma_f32 v17, v17, v77, v132
	v_fma_f32 v18, v18, v78, v132
	v_fma_f32 v19, v19, v79, v132
	v_fma_f32 v20, v20, v72, v132
	v_fma_f32 v21, v21, v73, v132
	v_fma_f32 v22, v22, v74, v132
	v_fma_f32 v23, v23, v75, v132
	v_fma_f32 v24, v24, v68, v132
	v_fma_f32 v25, v25, v69, v132
	v_fma_f32 v26, v26, v70, v132
	v_fma_f32 v27, v27, v71, v132
	v_fma_f32 v28, v28, v64, v132
	v_fma_f32 v29, v29, v65, v132
	v_fma_f32 v30, v30, v66, v132
	v_fmac_f32_e32 v132, v31, v67
	global_store_dwordx4 v[36:37], v[32:35], off offset:-4096
	v_mul_f32_e32 v16, 0xbfb8aa3b, v16
	v_mul_f32_e32 v17, 0xbfb8aa3b, v17
	v_mul_f32_e32 v18, 0xbfb8aa3b, v18
	v_mul_f32_e32 v19, 0xbfb8aa3b, v19
	v_mul_f32_e32 v20, 0xbfb8aa3b, v20
	v_mul_f32_e32 v21, 0xbfb8aa3b, v21
	v_mul_f32_e32 v22, 0xbfb8aa3b, v22
	v_mul_f32_e32 v23, 0xbfb8aa3b, v23
	v_mul_f32_e32 v24, 0xbfb8aa3b, v24
	v_mul_f32_e32 v25, 0xbfb8aa3b, v25
	v_mul_f32_e32 v26, 0xbfb8aa3b, v26
	v_mul_f32_e32 v27, 0xbfb8aa3b, v27
	v_mul_f32_e32 v28, 0xbfb8aa3b, v28
	v_mul_f32_e32 v29, 0xbfb8aa3b, v29
	v_mul_f32_e32 v30, 0xbfb8aa3b, v30
	v_mul_f32_e32 v31, 0xbfb8aa3b, v132
	v_exp_f32_e32 v16, v16
	v_exp_f32_e32 v17, v17
	v_exp_f32_e32 v18, v18
	v_exp_f32_e32 v19, v19
	v_exp_f32_e32 v20, v20
	v_exp_f32_e32 v21, v21
	v_exp_f32_e32 v22, v22
	v_exp_f32_e32 v23, v23
	v_exp_f32_e32 v24, v24
	v_exp_f32_e32 v25, v25
	v_exp_f32_e32 v26, v26
	v_exp_f32_e32 v27, v27
	v_exp_f32_e32 v28, v28
	v_exp_f32_e32 v29, v29
	v_exp_f32_e32 v30, v30
	v_exp_f32_e32 v31, v31
	v_add_f32_e32 v16, 1.0, v16
	v_add_f32_e32 v17, 1.0, v17
	v_add_f32_e32 v18, 1.0, v18
	v_add_f32_e32 v19, 1.0, v19
	v_add_f32_e32 v20, 1.0, v20
	v_add_f32_e32 v21, 1.0, v21
	v_add_f32_e32 v22, 1.0, v22
	v_add_f32_e32 v23, 1.0, v23
	v_add_f32_e32 v24, 1.0, v24
	v_add_f32_e32 v25, 1.0, v25
	v_add_f32_e32 v26, 1.0, v26
	v_add_f32_e32 v27, 1.0, v27
	v_add_f32_e32 v28, 1.0, v28
	v_add_f32_e32 v29, 1.0, v29
	v_add_f32_e32 v30, 1.0, v30
	v_add_f32_e32 v31, 1.0, v31
	v_rcp_f32_e32 v16, v16
	v_rcp_f32_e32 v17, v17
	v_rcp_f32_e32 v18, v18
	v_rcp_f32_e32 v19, v19
	v_rcp_f32_e32 v20, v20
	v_rcp_f32_e32 v21, v21
	v_rcp_f32_e32 v22, v22
	v_rcp_f32_e32 v23, v23
	v_rcp_f32_e32 v24, v24
	v_rcp_f32_e32 v25, v25
	v_rcp_f32_e32 v26, v26
	v_rcp_f32_e32 v27, v27
	v_rcp_f32_e32 v28, v28
	v_rcp_f32_e32 v29, v29
	v_rcp_f32_e32 v30, v30
	v_rcp_f32_e32 v31, v31
	v_cvt_pk_bf16_f32 v16, v16, v17
	v_cvt_pk_bf16_f32 v17, v18, v19
	v_cvt_pk_bf16_f32 v18, v20, v21
	v_cvt_pk_bf16_f32 v19, v22, v23
	v_add_co_u32_e32 v20, vcc, s33, v92
	v_fma_f32 v0, v0, v76, v48
	global_store_dwordx4 v[36:37], v[16:19], off
	v_addc_co_u32_e32 v21, vcc, 0, v93, vcc
	s_nop 0
	v_cvt_pk_bf16_f32 v16, v24, v25
	v_cvt_pk_bf16_f32 v17, v26, v27
	v_cvt_pk_bf16_f32 v18, v28, v29
	v_cvt_pk_bf16_f32 v19, v30, v31
	v_fma_f32 v1, v1, v77, v48
	v_fma_f32 v2, v2, v78, v48
	v_fma_f32 v3, v3, v79, v48
	v_fma_f32 v4, v4, v72, v48
	v_fma_f32 v5, v5, v73, v48
	v_fma_f32 v6, v6, v74, v48
	v_fma_f32 v7, v7, v75, v48
	v_fma_f32 v8, v8, v68, v48
	v_fma_f32 v9, v9, v69, v48
	v_fma_f32 v10, v10, v70, v48
	v_fma_f32 v11, v11, v71, v48
	v_fma_f32 v12, v12, v64, v48
	v_fma_f32 v13, v13, v65, v48
	v_fma_f32 v14, v14, v66, v48
	v_fmac_f32_e32 v48, v15, v67
	v_mul_f32_e32 v0, 0xbfb8aa3b, v0
	global_store_dwordx4 v[20:21], v[16:19], off offset:-4096
	v_mul_f32_e32 v1, 0xbfb8aa3b, v1
	v_mul_f32_e32 v2, 0xbfb8aa3b, v2
	v_mul_f32_e32 v3, 0xbfb8aa3b, v3
	v_mul_f32_e32 v4, 0xbfb8aa3b, v4
	v_mul_f32_e32 v5, 0xbfb8aa3b, v5
	v_mul_f32_e32 v6, 0xbfb8aa3b, v6
	v_mul_f32_e32 v7, 0xbfb8aa3b, v7
	v_mul_f32_e32 v8, 0xbfb8aa3b, v8
	v_mul_f32_e32 v9, 0xbfb8aa3b, v9
	v_mul_f32_e32 v10, 0xbfb8aa3b, v10
	v_mul_f32_e32 v11, 0xbfb8aa3b, v11
	v_mul_f32_e32 v12, 0xbfb8aa3b, v12
	v_mul_f32_e32 v13, 0xbfb8aa3b, v13
	v_mul_f32_e32 v14, 0xbfb8aa3b, v14
	v_mul_f32_e32 v15, 0xbfb8aa3b, v48
	v_exp_f32_e32 v0, v0
	v_exp_f32_e32 v1, v1
	v_exp_f32_e32 v2, v2
	v_exp_f32_e32 v3, v3
	v_exp_f32_e32 v4, v4
	v_exp_f32_e32 v5, v5
	v_exp_f32_e32 v6, v6
	v_exp_f32_e32 v7, v7
	v_exp_f32_e32 v8, v8
	v_exp_f32_e32 v9, v9
	v_exp_f32_e32 v10, v10
	v_exp_f32_e32 v11, v11
	v_exp_f32_e32 v12, v12
	v_exp_f32_e32 v13, v13
	v_exp_f32_e32 v14, v14
	v_exp_f32_e32 v15, v15
	v_add_f32_e32 v0, 1.0, v0
	v_rcp_f32_e32 v0, v0
	v_add_f32_e32 v1, 1.0, v1
	v_add_f32_e32 v2, 1.0, v2
	v_add_f32_e32 v3, 1.0, v3
	v_add_f32_e32 v4, 1.0, v4
	v_add_f32_e32 v5, 1.0, v5
	v_add_f32_e32 v6, 1.0, v6
	v_add_f32_e32 v7, 1.0, v7
	v_add_f32_e32 v8, 1.0, v8
	v_add_f32_e32 v9, 1.0, v9
	v_add_f32_e32 v10, 1.0, v10
	v_add_f32_e32 v11, 1.0, v11
	v_add_f32_e32 v12, 1.0, v12
	v_add_f32_e32 v13, 1.0, v13
	v_add_f32_e32 v14, 1.0, v14
	v_add_f32_e32 v15, 1.0, v15
	v_rcp_f32_e32 v1, v1
	v_rcp_f32_e32 v2, v2
	v_rcp_f32_e32 v3, v3
	v_rcp_f32_e32 v4, v4
	v_rcp_f32_e32 v5, v5
	v_rcp_f32_e32 v6, v6
	v_rcp_f32_e32 v7, v7
	v_rcp_f32_e32 v8, v8
	v_rcp_f32_e32 v9, v9
	v_rcp_f32_e32 v10, v10
	v_rcp_f32_e32 v11, v11
	v_rcp_f32_e32 v12, v12
	v_rcp_f32_e32 v13, v13
	v_rcp_f32_e32 v14, v14
	v_rcp_f32_e32 v15, v15
	v_cvt_pk_bf16_f32 v0, v0, v1
	v_cvt_pk_bf16_f32 v1, v2, v3
	v_cvt_pk_bf16_f32 v2, v4, v5
	v_cvt_pk_bf16_f32 v3, v6, v7
	v_add_co_u32_e32 v4, vcc, 0x7000, v92
	global_store_dwordx4 v[20:21], v[0:3], off
	s_nop 0
	v_addc_co_u32_e32 v5, vcc, 0, v93, vcc
	v_cvt_pk_bf16_f32 v0, v8, v9
	v_cvt_pk_bf16_f32 v1, v10, v11
	v_cvt_pk_bf16_f32 v2, v12, v13
	v_cvt_pk_bf16_f32 v3, v14, v15
	global_store_dwordx4 v[4:5], v[0:3], off
	s_cmp_eq_u32 s62, 1
	s_cbranch_scc0 .Lgt_e2
	s_mov_b32 s62, 2
	v_mov_b32_e32 v48, v136
	v_mov_b32_e32 v49, v137
	v_mov_b32_e32 v50, v138
	v_mov_b32_e32 v51, v139
	v_mov_b32_e32 v52, v140
	v_mov_b32_e32 v53, v141
	v_mov_b32_e32 v54, v142
	v_mov_b32_e32 v55, v143
	v_mov_b32_e32 v56, v144
	v_mov_b32_e32 v57, v145
	v_mov_b32_e32 v58, v146
	v_mov_b32_e32 v59, v147
	v_mov_b32_e32 v60, v148
	v_mov_b32_e32 v61, v149
	v_mov_b32_e32 v62, v150
	v_mov_b32_e32 v63, v151
	v_mov_b32_e32 v32, v152
	v_mov_b32_e32 v33, v153
	v_mov_b32_e32 v34, v154
	v_mov_b32_e32 v35, v155
	v_mov_b32_e32 v36, v156
	v_mov_b32_e32 v37, v157
	v_mov_b32_e32 v38, v158
	v_mov_b32_e32 v39, v159
	v_mov_b32_e32 v40, v160
	v_mov_b32_e32 v41, v161
	v_mov_b32_e32 v42, v162
	v_mov_b32_e32 v43, v163
	v_mov_b32_e32 v44, v164
	v_mov_b32_e32 v45, v165
	v_mov_b32_e32 v46, v166
	v_mov_b32_e32 v47, v167
	v_mov_b32_e32 v16, v168
	v_mov_b32_e32 v17, v169
	v_mov_b32_e32 v18, v170
	v_mov_b32_e32 v19, v171
	v_mov_b32_e32 v20, v172
	v_mov_b32_e32 v21, v173
	v_mov_b32_e32 v22, v174
	v_mov_b32_e32 v23, v175
	v_mov_b32_e32 v24, v176
	v_mov_b32_e32 v25, v177
	v_mov_b32_e32 v26, v178
	v_mov_b32_e32 v27, v179
	v_mov_b32_e32 v28, v180
	v_mov_b32_e32 v29, v181
	v_mov_b32_e32 v30, v182
	v_mov_b32_e32 v31, v183
	v_mov_b32_e32 v0, v184
	v_mov_b32_e32 v1, v185
	v_mov_b32_e32 v2, v186
	v_mov_b32_e32 v3, v187
	v_mov_b32_e32 v4, v188
	v_mov_b32_e32 v5, v189
	v_mov_b32_e32 v6, v190
	v_mov_b32_e32 v7, v191
	v_mov_b32_e32 v8, v192
	v_mov_b32_e32 v9, v193
	v_mov_b32_e32 v10, v194
	v_mov_b32_e32 v11, v195
	v_mov_b32_e32 v12, v196
	v_mov_b32_e32 v13, v197
	v_mov_b32_e32 v14, v198
	v_mov_b32_e32 v15, v199
	v_mov_b32_e32 v89, v200
	v_mov_b32_e32 v91, v201
	v_mov_b32_e32 v92, v202
	v_add_u32_e32 v93, 1, v203
	s_branch .LBB0_258
.Lgt_e2:
	s_mov_b32 s62, 0
	s_mov_b32 s63, s61
	s_mov_b64 s[16:17], -1
	s_nop 0
	v_mov_b32_e32 v0, v103
	s_andn2_b64 exec, exec, s[14:15]
	s_cbranch_execz .LBB0_275

.LBB0_263:
	s_or_b64 exec, exec, s[18:19]
	s_mov_b64 s[18:19], src_shared_base
	v_mov_b32_e32 v121, s19
	s_waitcnt lgkmcnt(0)
	s_barrier
	flat_load_dword v103, v[120:121] sc0 sc1
	s_waitcnt vmcnt(0)
	s_mov_b32 s61, 0
	s_cmp_eq_u32 s98, 0
	s_cbranch_scc1 .Lgq_skip2
	v_readfirstlane_b32 s60, v103
	s_cmp_lt_u32 s60, 78
	s_cbranch_scc0 .Lgd_s2
	s_mov_b32 s61, 1
	s_mul_hi_u32 s13, s60, 0x2aaaaaab
	s_mul_i32 s18, s13, 6
	s_sub_i32 s18, s60, s18
	s_lshl_b32 s13, s13, 1
	s_branch .Lgd_e2
.Lgd_s2:
	s_add_i32 s18, s60, 0xffffffb2
	s_cmp_lt_u32 s18, 36
	s_cbranch_scc0 .Lgd_x2
	s_mul_hi_u32 s13, s18, 0x2aaaaaab
	s_mul_i32 s19, s13, 6
	s_sub_i32 s18, s18, s19
	s_add_i32 s13, s13, 26
.Lgd_e2:
	s_mul_i32 s13, s13, 48
	s_lshl_b32 s18, s18, 3
	s_add_i32 s13, s13, s18
	s_add_i32 s13, s13, s99
	s_branch .Lgd_d2

.Lgd_d2:
	v_mov_b32_e32 v103, s13

.LBB0_267:
	s_or_b64 exec, exec, s[18:19]
	v_and_b32_e32 v93, 0xffff, v1
	v_mov_b32_e32 v1, 0xe00
	v_lshl_add_u32 v4, v93, 7, v1
	v_add_u32_e32 v1, 0xfffff000, v92
	v_lshrrev_b32_e32 v1, 10, v1
	v_add_u32_e32 v1, 1, v1
	v_cmp_lt_u16_e32 vcc, 31, v0
	s_mul_i32 s13, s12, 3
	v_mov_b64_e32 v[2:3], s[10:11]
	v_cndmask_b32_e32 v1, 0, v1, vcc
	v_add_u32_e32 v1, s13, v1
	s_mov_b32 s13, 0xd000
	v_mad_u64_u32 v[2:3], s[18:19], v1, s13, v[2:3]
	v_lshlrev_b32_e32 v116, 2, v4
	v_lshl_add_u64 v[2:3], v[2:3], 0, v[116:117]
	v_mov_b32_e32 v89, v117
	v_lshl_add_u64 v[2:3], v[2:3], 0, v[88:89]
	v_mov_b32_e32 v91, v117
	v_lshl_add_u64 v[2:3], v[2:3], 0, v[90:91]
	global_load_dword v89, v[2:3], off
	global_load_dword v91, v[2:3], off offset:128
	global_load_dword v200, v[2:3], off offset:512
	global_load_dword v201, v[2:3], off offset:640
	v_mov_b32_e32 v1, s31
	v_lshlrev_b64 v[0:1], 18, v[0:1]
	v_lshlrev_b32_e32 v116, 11, v4
	v_lshl_add_u64 v[64:65], v[80:81], 0, v[0:1]
	v_lshl_add_u64 v[66:67], v[82:83], 0, v[116:117]
	s_mov_b64 s[18:19], -1
	s_andn2_b64 vcc, exec, s[16:17]
	v_add_u32_e32 v79, 0x400, v94
	v_add_u32_e32 v78, 0x2000, v94
	v_add_u32_e32 v77, 0x2400, v94
	v_add_u32_e32 v76, 0x4000, v94
	v_add_u32_e32 v75, 0x4400, v94
	v_add_u32_e32 v74, 0x6000, v94
	v_add_u32_e32 v72, 0x6400, v94
	v_add_u32_e32 v71, 0x8000, v94
	v_add_u32_e32 v70, 0x8400, v94
	v_add_u32_e32 v69, 0xa000, v94
	v_add_u32_e32 v68, 0xa400, v94
	s_cbranch_vccnz .LBB0_269
	v_readfirstlane_b32 s13, v94
	s_mov_b32 m0, s13
	s_mov_b64 s[16:17], 0x400
	v_readfirstlane_b32 s13, v79
	global_load_lds_dwordx4 v[64:65], off
	v_lshl_add_u64 v[0:1], v[64:65], 0, s[16:17]
	s_mov_b32 m0, s13
	v_readfirstlane_b32 s13, v78
	global_load_lds_dwordx4 v[0:1], off
	s_mov_b32 m0, s13
	v_readfirstlane_b32 s13, v77
	global_load_lds_dwordx4 v[66:67], off
	v_lshl_add_u64 v[0:1], v[66:67], 0, s[16:17]
	s_mov_b32 m0, s13
	v_readfirstlane_b32 s13, v76
	global_load_lds_dwordx4 v[0:1], off
	v_lshl_add_u64 v[0:1], v[64:65], 0, s[44:45]
	s_mov_b32 m0, s13
	v_readfirstlane_b32 s13, v75
	global_load_lds_dwordx4 v[0:1], off
	v_lshl_add_u64 v[0:1], v[64:65], 0, s[66:67]
	s_mov_b32 m0, s13
	v_readfirstlane_b32 s13, v74
	global_load_lds_dwordx4 v[0:1], off
	v_lshl_add_u64 v[0:1], v[66:67], 0, s[44:45]
	s_mov_b32 m0, s13
	v_readfirstlane_b32 s13, v72
	global_load_lds_dwordx4 v[0:1], off
	v_lshl_add_u64 v[0:1], v[66:67], 0, s[66:67]
	s_mov_b32 m0, s13
	v_readfirstlane_b32 s13, v71
	global_load_lds_dwordx4 v[0:1], off
	v_lshl_add_u64 v[0:1], v[64:65], 0, s[28:29]
	s_mov_b32 m0, s13
	s_mov_b64 s[16:17], 0x4400
	v_readfirstlane_b32 s13, v70
	global_load_lds_dwordx4 v[0:1], off
	v_lshl_add_u64 v[0:1], v[64:65], 0, s[16:17]
	s_mov_b32 m0, s13
	v_readfirstlane_b32 s13, v69
	global_load_lds_dwordx4 v[0:1], off
	v_lshl_add_u64 v[0:1], v[66:67], 0, s[28:29]
	s_mov_b32 m0, s13
	v_readfirstlane_b32 s13, v68
	global_load_lds_dwordx4 v[0:1], off
	v_lshl_add_u64 v[0:1], v[66:67], 0, s[16:17]
	s_mov_b32 m0, s13
	s_mov_b64 s[18:19], 0
	global_load_lds_dwordx4 v[0:1], off
	s_waitcnt vmcnt(8)

.LBB0_271:
	s_cmp_eq_u32 s63, 1
	s_cbranch_scc1 .Lgt_pair
	s_mov_b32 s62, 0
	s_branch .Lgt_single
.Lgt_pair:
	s_mov_b32 s62, 1
	v_add_u32_e32 v116, v95, v99
	v_add_u32_e32 v119, v98, v99
	v_add_u32_e32 v122, v95, v100
	v_add_u32_e32 v125, v98, v100
	v_add_u32_e32 v243, 0x4000, v119
	v_add_u32_e32 v248, 0x4000, v125
	v_readfirstlane_b32 s50, v94
	s_mov_b64 s[72:73], 0x40000
	s_mov_b64 s[86:87], 0x4000
	s_add_u32 s51, s50, 0x4000
	s_add_u32 s52, s50, 0x8000
	s_add_u32 s53, s50, 0x2000
	s_add_u32 s54, s50, 0x6000
	s_add_u32 s55, s50, 0xa000
	s_add_u32 s56, s50, 0xc000
	s_add_u32 s57, s50, 0xe000
	s_add_u32 s58, s50, 0x12000
	v_lshl_add_u64 v[78:79], v[66:67], 0, s[72:73]
	s_mov_b32 m0, s56
	s_nop 0
	global_load_lds_dwordx4 v[78:79], off
	global_load_lds_dwordx4 v[78:79], off offset:1024
	v_lshl_add_u64 v[78:79], v[78:79], 0, s[44:45]
	s_mov_b32 m0, s57
	s_nop 0
	global_load_lds_dwordx4 v[78:79], off
	global_load_lds_dwordx4 v[78:79], off offset:1024
	v_lshl_add_u64 v[78:79], v[78:79], 0, s[44:45]
	s_mov_b32 m0, s58
	s_nop 0
	global_load_lds_dwordx4 v[78:79], off
	global_load_lds_dwordx4 v[78:79], off offset:1024
	v_lshl_add_u64 v[64:65], v[64:65], 0, s[86:87]
	v_lshl_add_u64 v[66:67], v[66:67], 0, s[86:87]
	s_waitcnt vmcnt(4)
	s_waitcnt lgkmcnt(0)
	s_barrier
	ds_read_b128 v[104:107], v116
	ds_read_b128 v[112:115], v119 offset:8192
	ds_read_b128 v[128:131], v119 offset:10240
	ds_read_b128 v[132:135], v119 offset:49152
	ds_read_b128 v[204:207], v119 offset:51200
	ds_read_b128 v[108:111], v116 offset:2048
	ds_read_b128 v[208:211], v122
	ds_read_b128 v[244:247], v125 offset:8192
	ds_read_b128 v[250:253], v125 offset:10240
	ds_read_b128 v[68:71], v125 offset:49152
	ds_read_b128 v[214:217], v122 offset:2048
	ds_read_b128 v[74:77], v125 offset:51200
	s_waitcnt lgkmcnt(6)
	v_mfma_f32_32x32x16_bf16 v[48:63], v[104:107], v[112:115], 0
	v_mfma_f32_32x32x16_bf16 v[32:47], v[104:107], v[128:131], 0
	v_mfma_f32_32x32x16_bf16 v[136:151], v[104:107], v[132:135], 0
	v_mfma_f32_32x32x16_bf16 v[152:167], v[104:107], v[204:207], 0
	v_mfma_f32_32x32x16_bf16 v[16:31], v[108:111], v[112:115], 0
	v_mfma_f32_32x32x16_bf16 v[0:15], v[108:111], v[128:131], 0
	v_mfma_f32_32x32x16_bf16 v[168:183], v[108:111], v[132:135], 0
	v_mfma_f32_32x32x16_bf16 v[184:199], v[108:111], v[204:207], 0
	s_waitcnt vmcnt(2)
	s_waitcnt lgkmcnt(0)
	s_barrier
	ds_read_b128 v[104:107], v116 offset:16384
	ds_read_b128 v[112:115], v119 offset:24576
	v_mfma_f32_32x32x16_bf16 v[48:63], v[208:211], v[244:247], v[48:63]
	ds_read_b128 v[128:131], v119 offset:26624
	ds_read_b128 v[132:135], v243 offset:40960
	v_mfma_f32_32x32x16_bf16 v[32:47], v[208:211], v[250:253], v[32:47]
	ds_read_b128 v[204:207], v243 offset:43008
	ds_read_b128 v[108:111], v116 offset:18432
	v_mfma_f32_32x32x16_bf16 v[136:151], v[208:211], v[68:71], v[136:151]
	v_mfma_f32_32x32x16_bf16 v[152:167], v[208:211], v[74:77], v[152:167]
	ds_read_b128 v[208:211], v122 offset:16384
	v_mfma_f32_32x32x16_bf16 v[16:31], v[214:217], v[244:247], v[16:31]
	ds_read_b128 v[244:247], v125 offset:24576
	v_mfma_f32_32x32x16_bf16 v[0:15], v[214:217], v[250:253], v[0:15]
	ds_read_b128 v[250:253], v125 offset:26624
	v_mfma_f32_32x32x16_bf16 v[168:183], v[214:217], v[68:71], v[168:183]
	ds_read_b128 v[68:71], v248 offset:40960
	v_mfma_f32_32x32x16_bf16 v[184:199], v[214:217], v[74:77], v[184:199]
	ds_read_b128 v[214:217], v122 offset:18432
	ds_read_b128 v[74:77], v248 offset:43008
	s_waitcnt lgkmcnt(6)
	v_mfma_f32_32x32x16_bf16 v[48:63], v[104:107], v[112:115], v[48:63]
	s_mov_b32 m0, s50
	v_lshl_add_u64 v[64:65], v[64:65], 0, s[44:45]
	global_load_lds_dwordx4 v[64:65], off
	v_mfma_f32_32x32x16_bf16 v[32:47], v[104:107], v[128:131], v[32:47]
	global_load_lds_dwordx4 v[64:65], off offset:1024
	v_mfma_f32_32x32x16_bf16 v[136:151], v[104:107], v[132:135], v[136:151]
	s_mov_b32 m0, s53
	v_lshl_add_u64 v[66:67], v[66:67], 0, s[44:45]
	global_load_lds_dwordx4 v[66:67], off
	v_mfma_f32_32x32x16_bf16 v[152:167], v[104:107], v[204:207], v[152:167]
	global_load_lds_dwordx4 v[66:67], off offset:1024
	v_mfma_f32_32x32x16_bf16 v[16:31], v[108:111], v[112:115], v[16:31]
	s_mov_b32 m0, s56
	v_lshl_add_u64 v[78:79], v[66:67], 0, s[72:73]
	global_load_lds_dwordx4 v[78:79], off
	v_mfma_f32_32x32x16_bf16 v[0:15], v[108:111], v[128:131], v[0:15]
	global_load_lds_dwordx4 v[78:79], off offset:1024
	v_mfma_f32_32x32x16_bf16 v[168:183], v[108:111], v[132:135], v[168:183]
	v_mfma_f32_32x32x16_bf16 v[184:199], v[108:111], v[204:207], v[184:199]
	s_waitcnt vmcnt(6)
	s_waitcnt lgkmcnt(0)
	s_barrier
	ds_read_b128 v[104:107], v116 offset:32768
	ds_read_b128 v[112:115], v119 offset:40960
	v_mfma_f32_32x32x16_bf16 v[48:63], v[208:211], v[244:247], v[48:63]
	ds_read_b128 v[128:131], v119 offset:43008
	ds_read_b128 v[132:135], v243 offset:57344
	v_mfma_f32_32x32x16_bf16 v[32:47], v[208:211], v[250:253], v[32:47]
	ds_read_b128 v[204:207], v243 offset:59392
	ds_read_b128 v[108:111], v116 offset:34816
	v_mfma_f32_32x32x16_bf16 v[136:151], v[208:211], v[68:71], v[136:151]
	v_mfma_f32_32x32x16_bf16 v[152:167], v[208:211], v[74:77], v[152:167]
	ds_read_b128 v[208:211], v122 offset:32768
	v_mfma_f32_32x32x16_bf16 v[16:31], v[214:217], v[244:247], v[16:31]
	ds_read_b128 v[244:247], v125 offset:40960
	v_mfma_f32_32x32x16_bf16 v[0:15], v[214:217], v[250:253], v[0:15]
	ds_read_b128 v[250:253], v125 offset:43008
	v_mfma_f32_32x32x16_bf16 v[168:183], v[214:217], v[68:71], v[168:183]
	ds_read_b128 v[68:71], v248 offset:57344
	v_mfma_f32_32x32x16_bf16 v[184:199], v[214:217], v[74:77], v[184:199]
	ds_read_b128 v[214:217], v122 offset:34816
	ds_read_b128 v[74:77], v248 offset:59392
	s_waitcnt lgkmcnt(6)
	v_mfma_f32_32x32x16_bf16 v[48:63], v[104:107], v[112:115], v[48:63]
	s_mov_b32 m0, s51
	v_lshl_add_u64 v[64:65], v[64:65], 0, s[44:45]
	global_load_lds_dwordx4 v[64:65], off
	v_mfma_f32_32x32x16_bf16 v[32:47], v[104:107], v[128:131], v[32:47]
	global_load_lds_dwordx4 v[64:65], off offset:1024
	v_mfma_f32_32x32x16_bf16 v[136:151], v[104:107], v[132:135], v[136:151]
	s_mov_b32 m0, s54
	v_lshl_add_u64 v[66:67], v[66:67], 0, s[44:45]
	global_load_lds_dwordx4 v[66:67], off
	v_mfma_f32_32x32x16_bf16 v[152:167], v[104:107], v[204:207], v[152:167]
	global_load_lds_dwordx4 v[66:67], off offset:1024
	v_mfma_f32_32x32x16_bf16 v[16:31], v[108:111], v[112:115], v[16:31]
	s_mov_b32 m0, s57
	v_lshl_add_u64 v[78:79], v[66:67], 0, s[72:73]
	global_load_lds_dwordx4 v[78:79], off
	v_mfma_f32_32x32x16_bf16 v[0:15], v[108:111], v[128:131], v[0:15]
	global_load_lds_dwordx4 v[78:79], off offset:1024
	v_mfma_f32_32x32x16_bf16 v[168:183], v[108:111], v[132:135], v[168:183]
	v_mfma_f32_32x32x16_bf16 v[184:199], v[108:111], v[204:207], v[184:199]
	s_waitcnt vmcnt(6)
	s_waitcnt lgkmcnt(0)
	s_barrier
	ds_read_b128 v[104:107], v116
	ds_read_b128 v[112:115], v119 offset:8192
	v_mfma_f32_32x32x16_bf16 v[48:63], v[208:211], v[244:247], v[48:63]
	ds_read_b128 v[128:131], v119 offset:10240
	ds_read_b128 v[132:135], v119 offset:49152
	v_mfma_f32_32x32x16_bf16 v[32:47], v[208:211], v[250:253], v[32:47]
	ds_read_b128 v[204:207], v119 offset:51200
	ds_read_b128 v[108:111], v116 offset:2048
	v_mfma_f32_32x32x16_bf16 v[136:151], v[208:211], v[68:71], v[136:151]
	v_mfma_f32_32x32x16_bf16 v[152:167], v[208:211], v[74:77], v[152:167]
	ds_read_b128 v[208:211], v122
	v_mfma_f32_32x32x16_bf16 v[16:31], v[214:217], v[244:247], v[16:31]
	ds_read_b128 v[244:247], v125 offset:8192
	v_mfma_f32_32x32x16_bf16 v[0:15], v[214:217], v[250:253], v[0:15]
	ds_read_b128 v[250:253], v125 offset:10240
	v_mfma_f32_32x32x16_bf16 v[168:183], v[214:217], v[68:71], v[168:183]
	ds_read_b128 v[68:71], v125 offset:49152
	v_mfma_f32_32x32x16_bf16 v[184:199], v[214:217], v[74:77], v[184:199]
	ds_read_b128 v[214:217], v122 offset:2048
	ds_read_b128 v[74:77], v125 offset:51200
	s_waitcnt lgkmcnt(6)
	v_mfma_f32_32x32x16_bf16 v[48:63], v[104:107], v[112:115], v[48:63]
	s_mov_b32 m0, s52
	v_lshl_add_u64 v[64:65], v[64:65], 0, s[44:45]
	global_load_lds_dwordx4 v[64:65], off
	v_mfma_f32_32x32x16_bf16 v[32:47], v[104:107], v[128:131], v[32:47]
	global_load_lds_dwordx4 v[64:65], off offset:1024
	v_mfma_f32_32x32x16_bf16 v[136:151], v[104:107], v[132:135], v[136:151]
	s_mov_b32 m0, s55
	v_lshl_add_u64 v[66:67], v[66:67], 0, s[44:45]
	global_load_lds_dwordx4 v[66:67], off
	v_mfma_f32_32x32x16_bf16 v[152:167], v[104:107], v[204:207], v[152:167]
	global_load_lds_dwordx4 v[66:67], off offset:1024
	v_mfma_f32_32x32x16_bf16 v[16:31], v[108:111], v[112:115], v[16:31]
	s_mov_b32 m0, s58
	v_lshl_add_u64 v[78:79], v[66:67], 0, s[72:73]
	global_load_lds_dwordx4 v[78:79], off
	v_mfma_f32_32x32x16_bf16 v[0:15], v[108:111], v[128:131], v[0:15]
	global_load_lds_dwordx4 v[78:79], off offset:1024
	v_mfma_f32_32x32x16_bf16 v[168:183], v[108:111], v[132:135], v[168:183]
	v_mfma_f32_32x32x16_bf16 v[184:199], v[108:111], v[204:207], v[184:199]
	s_waitcnt vmcnt(6)
	s_waitcnt lgkmcnt(0)
	s_barrier
	ds_read_b128 v[104:107], v116 offset:16384
	ds_read_b128 v[112:115], v119 offset:24576
	v_mfma_f32_32x32x16_bf16 v[48:63], v[208:211], v[244:247], v[48:63]
	ds_read_b128 v[128:131], v119 offset:26624
	ds_read_b128 v[132:135], v243 offset:40960
	v_mfma_f32_32x32x16_bf16 v[32:47], v[208:211], v[250:253], v[32:47]
	ds_read_b128 v[204:207], v243 offset:43008
	ds_read_b128 v[108:111], v116 offset:18432
	v_mfma_f32_32x32x16_bf16 v[136:151], v[208:211], v[68:71], v[136:151]
	v_mfma_f32_32x32x16_bf16 v[152:167], v[208:211], v[74:77], v[152:167]
	ds_read_b128 v[208:211], v122 offset:16384
	v_mfma_f32_32x32x16_bf16 v[16:31], v[214:217], v[244:247], v[16:31]
	ds_read_b128 v[244:247], v125 offset:24576
	v_mfma_f32_32x32x16_bf16 v[0:15], v[214:217], v[250:253], v[0:15]
	ds_read_b128 v[250:253], v125 offset:26624
	v_mfma_f32_32x32x16_bf16 v[168:183], v[214:217], v[68:71], v[168:183]
	ds_read_b128 v[68:71], v248 offset:40960
	v_mfma_f32_32x32x16_bf16 v[184:199], v[214:217], v[74:77], v[184:199]
	ds_read_b128 v[214:217], v122 offset:18432
	ds_read_b128 v[74:77], v248 offset:43008
	s_waitcnt lgkmcnt(6)
	v_mfma_f32_32x32x16_bf16 v[48:63], v[104:107], v[112:115], v[48:63]
	s_mov_b32 m0, s50
	v_lshl_add_u64 v[64:65], v[64:65], 0, s[44:45]
	global_load_lds_dwordx4 v[64:65], off
	v_mfma_f32_32x32x16_bf16 v[32:47], v[104:107], v[128:131], v[32:47]
	global_load_lds_dwordx4 v[64:65], off offset:1024
	v_mfma_f32_32x32x16_bf16 v[136:151], v[104:107], v[132:135], v[136:151]
	s_mov_b32 m0, s53
	v_lshl_add_u64 v[66:67], v[66:67], 0, s[44:45]
	global_load_lds_dwordx4 v[66:67], off
	v_mfma_f32_32x32x16_bf16 v[152:167], v[104:107], v[204:207], v[152:167]
	global_load_lds_dwordx4 v[66:67], off offset:1024
	v_mfma_f32_32x32x16_bf16 v[16:31], v[108:111], v[112:115], v[16:31]
	s_mov_b32 m0, s56
	v_lshl_add_u64 v[78:79], v[66:67], 0, s[72:73]
	global_load_lds_dwordx4 v[78:79], off
	v_mfma_f32_32x32x16_bf16 v[0:15], v[108:111], v[128:131], v[0:15]
	global_load_lds_dwordx4 v[78:79], off offset:1024
	v_mfma_f32_32x32x16_bf16 v[168:183], v[108:111], v[132:135], v[168:183]
	v_mfma_f32_32x32x16_bf16 v[184:199], v[108:111], v[204:207], v[184:199]
	s_waitcnt vmcnt(6)
	s_waitcnt lgkmcnt(0)
	s_barrier
	ds_read_b128 v[104:107], v116 offset:32768
	ds_read_b128 v[112:115], v119 offset:40960
	v_mfma_f32_32x32x16_bf16 v[48:63], v[208:211], v[244:247], v[48:63]
	ds_read_b128 v[128:131], v119 offset:43008
	ds_read_b128 v[132:135], v243 offset:57344
	v_mfma_f32_32x32x16_bf16 v[32:47], v[208:211], v[250:253], v[32:47]
	ds_read_b128 v[204:207], v243 offset:59392
	ds_read_b128 v[108:111], v116 offset:34816
	v_mfma_f32_32x32x16_bf16 v[136:151], v[208:211], v[68:71], v[136:151]
	v_mfma_f32_32x32x16_bf16 v[152:167], v[208:211], v[74:77], v[152:167]
	ds_read_b128 v[208:211], v122 offset:32768
	v_mfma_f32_32x32x16_bf16 v[16:31], v[214:217], v[244:247], v[16:31]
	ds_read_b128 v[244:247], v125 offset:40960
	v_mfma_f32_32x32x16_bf16 v[0:15], v[214:217], v[250:253], v[0:15]
	ds_read_b128 v[250:253], v125 offset:43008
	v_mfma_f32_32x32x16_bf16 v[168:183], v[214:217], v[68:71], v[168:183]
	ds_read_b128 v[68:71], v248 offset:57344
	v_mfma_f32_32x32x16_bf16 v[184:199], v[214:217], v[74:77], v[184:199]
	ds_read_b128 v[214:217], v122 offset:34816
	ds_read_b128 v[74:77], v248 offset:59392
	s_waitcnt lgkmcnt(6)
	v_mfma_f32_32x32x16_bf16 v[48:63], v[104:107], v[112:115], v[48:63]
	s_mov_b32 m0, s51
	v_lshl_add_u64 v[64:65], v[64:65], 0, s[44:45]
	global_load_lds_dwordx4 v[64:65], off
	v_mfma_f32_32x32x16_bf16 v[32:47], v[104:107], v[128:131], v[32:47]
	global_load_lds_dwordx4 v[64:65], off offset:1024
	v_mfma_f32_32x32x16_bf16 v[136:151], v[104:107], v[132:135], v[136:151]
	s_mov_b32 m0, s54
	v_lshl_add_u64 v[66:67], v[66:67], 0, s[44:45]
	global_load_lds_dwordx4 v[66:67], off
	v_mfma_f32_32x32x16_bf16 v[152:167], v[104:107], v[204:207], v[152:167]
	global_load_lds_dwordx4 v[66:67], off offset:1024
	v_mfma_f32_32x32x16_bf16 v[16:31], v[108:111], v[112:115], v[16:31]
	s_mov_b32 m0, s57
	v_lshl_add_u64 v[78:79], v[66:67], 0, s[72:73]
	global_load_lds_dwordx4 v[78:79], off
	v_mfma_f32_32x32x16_bf16 v[0:15], v[108:111], v[128:131], v[0:15]
	global_load_lds_dwordx4 v[78:79], off offset:1024
	v_mfma_f32_32x32x16_bf16 v[168:183], v[108:111], v[132:135], v[168:183]
	v_mfma_f32_32x32x16_bf16 v[184:199], v[108:111], v[204:207], v[184:199]
	s_waitcnt vmcnt(6)
	s_waitcnt lgkmcnt(0)
	s_barrier
	ds_read_b128 v[104:107], v116
	ds_read_b128 v[112:115], v119 offset:8192
	v_mfma_f32_32x32x16_bf16 v[48:63], v[208:211], v[244:247], v[48:63]
	ds_read_b128 v[128:131], v119 offset:10240
	ds_read_b128 v[132:135], v119 offset:49152
	v_mfma_f32_32x32x16_bf16 v[32:47], v[208:211], v[250:253], v[32:47]
	ds_read_b128 v[204:207], v119 offset:51200
	ds_read_b128 v[108:111], v116 offset:2048
	v_mfma_f32_32x32x16_bf16 v[136:151], v[208:211], v[68:71], v[136:151]
	v_mfma_f32_32x32x16_bf16 v[152:167], v[208:211], v[74:77], v[152:167]
	ds_read_b128 v[208:211], v122
	v_mfma_f32_32x32x16_bf16 v[16:31], v[214:217], v[244:247], v[16:31]
	ds_read_b128 v[244:247], v125 offset:8192
	v_mfma_f32_32x32x16_bf16 v[0:15], v[214:217], v[250:253], v[0:15]
	ds_read_b128 v[250:253], v125 offset:10240
	v_mfma_f32_32x32x16_bf16 v[168:183], v[214:217], v[68:71], v[168:183]
	ds_read_b128 v[68:71], v125 offset:49152
	v_mfma_f32_32x32x16_bf16 v[184:199], v[214:217], v[74:77], v[184:199]
	ds_read_b128 v[214:217], v122 offset:2048
	ds_read_b128 v[74:77], v125 offset:51200
	s_waitcnt lgkmcnt(6)
	v_mfma_f32_32x32x16_bf16 v[48:63], v[104:107], v[112:115], v[48:63]
	s_mov_b32 m0, s52
	v_lshl_add_u64 v[64:65], v[64:65], 0, s[44:45]
	global_load_lds_dwordx4 v[64:65], off
	v_mfma_f32_32x32x16_bf16 v[32:47], v[104:107], v[128:131], v[32:47]
	global_load_lds_dwordx4 v[64:65], off offset:1024
	v_mfma_f32_32x32x16_bf16 v[136:151], v[104:107], v[132:135], v[136:151]
	s_mov_b32 m0, s55
	v_lshl_add_u64 v[66:67], v[66:67], 0, s[44:45]
	global_load_lds_dwordx4 v[66:67], off
	v_mfma_f32_32x32x16_bf16 v[152:167], v[104:107], v[204:207], v[152:167]
	global_load_lds_dwordx4 v[66:67], off offset:1024
	v_mfma_f32_32x32x16_bf16 v[16:31], v[108:111], v[112:115], v[16:31]
	s_mov_b32 m0, s58
	v_lshl_add_u64 v[78:79], v[66:67], 0, s[72:73]
	global_load_lds_dwordx4 v[78:79], off
	v_mfma_f32_32x32x16_bf16 v[0:15], v[108:111], v[128:131], v[0:15]
	global_load_lds_dwordx4 v[78:79], off offset:1024
	v_mfma_f32_32x32x16_bf16 v[168:183], v[108:111], v[132:135], v[168:183]
	v_mfma_f32_32x32x16_bf16 v[184:199], v[108:111], v[204:207], v[184:199]
	s_waitcnt vmcnt(6)
	s_waitcnt lgkmcnt(0)
	s_barrier
	ds_read_b128 v[104:107], v116 offset:16384
	ds_read_b128 v[112:115], v119 offset:24576
	v_mfma_f32_32x32x16_bf16 v[48:63], v[208:211], v[244:247], v[48:63]
	ds_read_b128 v[128:131], v119 offset:26624
	ds_read_b128 v[132:135], v243 offset:40960
	v_mfma_f32_32x32x16_bf16 v[32:47], v[208:211], v[250:253], v[32:47]
	ds_read_b128 v[204:207], v243 offset:43008
	ds_read_b128 v[108:111], v116 offset:18432
	v_mfma_f32_32x32x16_bf16 v[136:151], v[208:211], v[68:71], v[136:151]
	v_mfma_f32_32x32x16_bf16 v[152:167], v[208:211], v[74:77], v[152:167]
	ds_read_b128 v[208:211], v122 offset:16384
	v_mfma_f32_32x32x16_bf16 v[16:31], v[214:217], v[244:247], v[16:31]
	ds_read_b128 v[244:247], v125 offset:24576
	v_mfma_f32_32x32x16_bf16 v[0:15], v[214:217], v[250:253], v[0:15]
	ds_read_b128 v[250:253], v125 offset:26624
	v_mfma_f32_32x32x16_bf16 v[168:183], v[214:217], v[68:71], v[168:183]
	ds_read_b128 v[68:71], v248 offset:40960
	v_mfma_f32_32x32x16_bf16 v[184:199], v[214:217], v[74:77], v[184:199]
	ds_read_b128 v[214:217], v122 offset:18432
	ds_read_b128 v[74:77], v248 offset:43008
	s_waitcnt lgkmcnt(6)
	v_mfma_f32_32x32x16_bf16 v[48:63], v[104:107], v[112:115], v[48:63]
	s_mov_b32 m0, s50
	v_lshl_add_u64 v[64:65], v[64:65], 0, s[44:45]
	global_load_lds_dwordx4 v[64:65], off
	v_mfma_f32_32x32x16_bf16 v[32:47], v[104:107], v[128:131], v[32:47]
	global_load_lds_dwordx4 v[64:65], off offset:1024
	v_mfma_f32_32x32x16_bf16 v[136:151], v[104:107], v[132:135], v[136:151]
	s_mov_b32 m0, s53
	v_lshl_add_u64 v[66:67], v[66:67], 0, s[44:45]
	global_load_lds_dwordx4 v[66:67], off
	v_mfma_f32_32x32x16_bf16 v[152:167], v[104:107], v[204:207], v[152:167]
	global_load_lds_dwordx4 v[66:67], off offset:1024
	v_mfma_f32_32x32x16_bf16 v[16:31], v[108:111], v[112:115], v[16:31]
	s_mov_b32 m0, s56
	v_lshl_add_u64 v[78:79], v[66:67], 0, s[72:73]
	global_load_lds_dwordx4 v[78:79], off
	v_mfma_f32_32x32x16_bf16 v[0:15], v[108:111], v[128:131], v[0:15]
	global_load_lds_dwordx4 v[78:79], off offset:1024
	v_mfma_f32_32x32x16_bf16 v[168:183], v[108:111], v[132:135], v[168:183]
	v_mfma_f32_32x32x16_bf16 v[184:199], v[108:111], v[204:207], v[184:199]
	s_waitcnt vmcnt(6)
	s_waitcnt lgkmcnt(0)
	s_barrier
	ds_read_b128 v[104:107], v116 offset:32768
	ds_read_b128 v[112:115], v119 offset:40960
	v_mfma_f32_32x32x16_bf16 v[48:63], v[208:211], v[244:247], v[48:63]
	ds_read_b128 v[128:131], v119 offset:43008
	ds_read_b128 v[132:135], v243 offset:57344
	v_mfma_f32_32x32x16_bf16 v[32:47], v[208:211], v[250:253], v[32:47]
	ds_read_b128 v[204:207], v243 offset:59392
	ds_read_b128 v[108:111], v116 offset:34816
	v_mfma_f32_32x32x16_bf16 v[136:151], v[208:211], v[68:71], v[136:151]
	v_mfma_f32_32x32x16_bf16 v[152:167], v[208:211], v[74:77], v[152:167]
	ds_read_b128 v[208:211], v122 offset:32768
	v_mfma_f32_32x32x16_bf16 v[16:31], v[214:217], v[244:247], v[16:31]
	ds_read_b128 v[244:247], v125 offset:40960
	v_mfma_f32_32x32x16_bf16 v[0:15], v[214:217], v[250:253], v[0:15]
	ds_read_b128 v[250:253], v125 offset:43008
	v_mfma_f32_32x32x16_bf16 v[168:183], v[214:217], v[68:71], v[168:183]
	ds_read_b128 v[68:71], v248 offset:57344
	v_mfma_f32_32x32x16_bf16 v[184:199], v[214:217], v[74:77], v[184:199]
	ds_read_b128 v[214:217], v122 offset:34816
	ds_read_b128 v[74:77], v248 offset:59392
	s_waitcnt lgkmcnt(6)
	v_mfma_f32_32x32x16_bf16 v[48:63], v[104:107], v[112:115], v[48:63]
	s_mov_b32 m0, s51
	v_lshl_add_u64 v[64:65], v[64:65], 0, s[44:45]
	global_load_lds_dwordx4 v[64:65], off
	v_mfma_f32_32x32x16_bf16 v[32:47], v[104:107], v[128:131], v[32:47]
	global_load_lds_dwordx4 v[64:65], off offset:1024
	v_mfma_f32_32x32x16_bf16 v[136:151], v[104:107], v[132:135], v[136:151]
	s_mov_b32 m0, s54
	v_lshl_add_u64 v[66:67], v[66:67], 0, s[44:45]
	global_load_lds_dwordx4 v[66:67], off
	v_mfma_f32_32x32x16_bf16 v[152:167], v[104:107], v[204:207], v[152:167]
	global_load_lds_dwordx4 v[66:67], off offset:1024
	v_mfma_f32_32x32x16_bf16 v[16:31], v[108:111], v[112:115], v[16:31]
	s_mov_b32 m0, s57
	v_lshl_add_u64 v[78:79], v[66:67], 0, s[72:73]
	global_load_lds_dwordx4 v[78:79], off
	v_mfma_f32_32x32x16_bf16 v[0:15], v[108:111], v[128:131], v[0:15]
	global_load_lds_dwordx4 v[78:79], off offset:1024
	v_mfma_f32_32x32x16_bf16 v[168:183], v[108:111], v[132:135], v[168:183]
	v_mfma_f32_32x32x16_bf16 v[184:199], v[108:111], v[204:207], v[184:199]
	s_waitcnt vmcnt(6)
	s_waitcnt lgkmcnt(0)
	s_barrier
	ds_read_b128 v[104:107], v116
	ds_read_b128 v[112:115], v119 offset:8192
	v_mfma_f32_32x32x16_bf16 v[48:63], v[208:211], v[244:247], v[48:63]
	ds_read_b128 v[128:131], v119 offset:10240
	ds_read_b128 v[132:135], v119 offset:49152
	v_mfma_f32_32x32x16_bf16 v[32:47], v[208:211], v[250:253], v[32:47]
	ds_read_b128 v[204:207], v119 offset:51200
	ds_read_b128 v[108:111], v116 offset:2048
	v_mfma_f32_32x32x16_bf16 v[136:151], v[208:211], v[68:71], v[136:151]
	v_mfma_f32_32x32x16_bf16 v[152:167], v[208:211], v[74:77], v[152:167]
	ds_read_b128 v[208:211], v122
	v_mfma_f32_32x32x16_bf16 v[16:31], v[214:217], v[244:247], v[16:31]
	ds_read_b128 v[244:247], v125 offset:8192
	v_mfma_f32_32x32x16_bf16 v[0:15], v[214:217], v[250:253], v[0:15]
	ds_read_b128 v[250:253], v125 offset:10240
	v_mfma_f32_32x32x16_bf16 v[168:183], v[214:217], v[68:71], v[168:183]
	ds_read_b128 v[68:71], v125 offset:49152
	v_mfma_f32_32x32x16_bf16 v[184:199], v[214:217], v[74:77], v[184:199]
	ds_read_b128 v[214:217], v122 offset:2048
	ds_read_b128 v[74:77], v125 offset:51200
	s_waitcnt lgkmcnt(6)
	v_mfma_f32_32x32x16_bf16 v[48:63], v[104:107], v[112:115], v[48:63]
	s_mov_b32 m0, s52
	v_lshl_add_u64 v[64:65], v[64:65], 0, s[44:45]
	global_load_lds_dwordx4 v[64:65], off
	v_mfma_f32_32x32x16_bf16 v[32:47], v[104:107], v[128:131], v[32:47]
	global_load_lds_dwordx4 v[64:65], off offset:1024
	v_mfma_f32_32x32x16_bf16 v[136:151], v[104:107], v[132:135], v[136:151]
	s_mov_b32 m0, s55
	v_lshl_add_u64 v[66:67], v[66:67], 0, s[44:45]
	global_load_lds_dwordx4 v[66:67], off
	v_mfma_f32_32x32x16_bf16 v[152:167], v[104:107], v[204:207], v[152:167]
	global_load_lds_dwordx4 v[66:67], off offset:1024
	v_mfma_f32_32x32x16_bf16 v[16:31], v[108:111], v[112:115], v[16:31]
	s_mov_b32 m0, s58
	v_lshl_add_u64 v[78:79], v[66:67], 0, s[72:73]
	global_load_lds_dwordx4 v[78:79], off
	v_mfma_f32_32x32x16_bf16 v[0:15], v[108:111], v[128:131], v[0:15]
	global_load_lds_dwordx4 v[78:79], off offset:1024
	v_mfma_f32_32x32x16_bf16 v[168:183], v[108:111], v[132:135], v[168:183]
	v_mfma_f32_32x32x16_bf16 v[184:199], v[108:111], v[204:207], v[184:199]
	s_waitcnt vmcnt(6)
	s_waitcnt lgkmcnt(0)
	s_barrier
	ds_read_b128 v[104:107], v116 offset:16384
	ds_read_b128 v[112:115], v119 offset:24576
	v_mfma_f32_32x32x16_bf16 v[48:63], v[208:211], v[244:247], v[48:63]
	ds_read_b128 v[128:131], v119 offset:26624
	ds_read_b128 v[132:135], v243 offset:40960
	v_mfma_f32_32x32x16_bf16 v[32:47], v[208:211], v[250:253], v[32:47]
	ds_read_b128 v[204:207], v243 offset:43008
	ds_read_b128 v[108:111], v116 offset:18432
	v_mfma_f32_32x32x16_bf16 v[136:151], v[208:211], v[68:71], v[136:151]
	v_mfma_f32_32x32x16_bf16 v[152:167], v[208:211], v[74:77], v[152:167]
	ds_read_b128 v[208:211], v122 offset:16384
	v_mfma_f32_32x32x16_bf16 v[16:31], v[214:217], v[244:247], v[16:31]
	ds_read_b128 v[244:247], v125 offset:24576
	v_mfma_f32_32x32x16_bf16 v[0:15], v[214:217], v[250:253], v[0:15]
	ds_read_b128 v[250:253], v125 offset:26624
	v_mfma_f32_32x32x16_bf16 v[168:183], v[214:217], v[68:71], v[168:183]
	ds_read_b128 v[68:71], v248 offset:40960
	v_mfma_f32_32x32x16_bf16 v[184:199], v[214:217], v[74:77], v[184:199]
	ds_read_b128 v[214:217], v122 offset:18432
	ds_read_b128 v[74:77], v248 offset:43008
	s_waitcnt lgkmcnt(6)
	v_mfma_f32_32x32x16_bf16 v[48:63], v[104:107], v[112:115], v[48:63]
	s_mov_b32 m0, s50
	v_lshl_add_u64 v[64:65], v[64:65], 0, s[44:45]
	global_load_lds_dwordx4 v[64:65], off
	v_mfma_f32_32x32x16_bf16 v[32:47], v[104:107], v[128:131], v[32:47]
	global_load_lds_dwordx4 v[64:65], off offset:1024
	v_mfma_f32_32x32x16_bf16 v[136:151], v[104:107], v[132:135], v[136:151]
	s_mov_b32 m0, s53
	v_lshl_add_u64 v[66:67], v[66:67], 0, s[44:45]
	global_load_lds_dwordx4 v[66:67], off
	v_mfma_f32_32x32x16_bf16 v[152:167], v[104:107], v[204:207], v[152:167]
	global_load_lds_dwordx4 v[66:67], off offset:1024
	v_mfma_f32_32x32x16_bf16 v[16:31], v[108:111], v[112:115], v[16:31]
	s_mov_b32 m0, s56
	v_lshl_add_u64 v[78:79], v[66:67], 0, s[72:73]
	global_load_lds_dwordx4 v[78:79], off
	v_mfma_f32_32x32x16_bf16 v[0:15], v[108:111], v[128:131], v[0:15]
	global_load_lds_dwordx4 v[78:79], off offset:1024
	v_mfma_f32_32x32x16_bf16 v[168:183], v[108:111], v[132:135], v[168:183]
	v_mfma_f32_32x32x16_bf16 v[184:199], v[108:111], v[204:207], v[184:199]
	s_waitcnt vmcnt(6)
	s_waitcnt lgkmcnt(0)
	s_barrier
	ds_read_b128 v[104:107], v116 offset:32768
	ds_read_b128 v[112:115], v119 offset:40960
	v_mfma_f32_32x32x16_bf16 v[48:63], v[208:211], v[244:247], v[48:63]
	ds_read_b128 v[128:131], v119 offset:43008
	ds_read_b128 v[132:135], v243 offset:57344
	v_mfma_f32_32x32x16_bf16 v[32:47], v[208:211], v[250:253], v[32:47]
	ds_read_b128 v[204:207], v243 offset:59392
	ds_read_b128 v[108:111], v116 offset:34816
	v_mfma_f32_32x32x16_bf16 v[136:151], v[208:211], v[68:71], v[136:151]
	v_mfma_f32_32x32x16_bf16 v[152:167], v[208:211], v[74:77], v[152:167]
	ds_read_b128 v[208:211], v122 offset:32768
	v_mfma_f32_32x32x16_bf16 v[16:31], v[214:217], v[244:247], v[16:31]
	ds_read_b128 v[244:247], v125 offset:40960
	v_mfma_f32_32x32x16_bf16 v[0:15], v[214:217], v[250:253], v[0:15]
	ds_read_b128 v[250:253], v125 offset:43008
	v_mfma_f32_32x32x16_bf16 v[168:183], v[214:217], v[68:71], v[168:183]
	ds_read_b128 v[68:71], v248 offset:57344
	v_mfma_f32_32x32x16_bf16 v[184:199], v[214:217], v[74:77], v[184:199]
	ds_read_b128 v[214:217], v122 offset:34816
	ds_read_b128 v[74:77], v248 offset:59392
	s_waitcnt lgkmcnt(6)
	v_mfma_f32_32x32x16_bf16 v[48:63], v[104:107], v[112:115], v[48:63]
	s_mov_b32 m0, s51
	v_lshl_add_u64 v[64:65], v[64:65], 0, s[44:45]
	global_load_lds_dwordx4 v[64:65], off
	v_mfma_f32_32x32x16_bf16 v[32:47], v[104:107], v[128:131], v[32:47]
	global_load_lds_dwordx4 v[64:65], off offset:1024
	v_mfma_f32_32x32x16_bf16 v[136:151], v[104:107], v[132:135], v[136:151]
	s_mov_b32 m0, s54
	v_lshl_add_u64 v[66:67], v[66:67], 0, s[44:45]
	global_load_lds_dwordx4 v[66:67], off
	v_mfma_f32_32x32x16_bf16 v[152:167], v[104:107], v[204:207], v[152:167]
	global_load_lds_dwordx4 v[66:67], off offset:1024
	v_mfma_f32_32x32x16_bf16 v[16:31], v[108:111], v[112:115], v[16:31]
	s_mov_b32 m0, s57
	v_lshl_add_u64 v[78:79], v[66:67], 0, s[72:73]
	global_load_lds_dwordx4 v[78:79], off
	v_mfma_f32_32x32x16_bf16 v[0:15], v[108:111], v[128:131], v[0:15]
	global_load_lds_dwordx4 v[78:79], off offset:1024
	v_mfma_f32_32x32x16_bf16 v[168:183], v[108:111], v[132:135], v[168:183]
	v_mfma_f32_32x32x16_bf16 v[184:199], v[108:111], v[204:207], v[184:199]
	s_waitcnt vmcnt(6)
	s_waitcnt lgkmcnt(0)
	s_barrier
	ds_read_b128 v[104:107], v116
	ds_read_b128 v[112:115], v119 offset:8192
	v_mfma_f32_32x32x16_bf16 v[48:63], v[208:211], v[244:247], v[48:63]
	ds_read_b128 v[128:131], v119 offset:10240
	ds_read_b128 v[132:135], v119 offset:49152
	v_mfma_f32_32x32x16_bf16 v[32:47], v[208:211], v[250:253], v[32:47]
	ds_read_b128 v[204:207], v119 offset:51200
	ds_read_b128 v[108:111], v116 offset:2048
	v_mfma_f32_32x32x16_bf16 v[136:151], v[208:211], v[68:71], v[136:151]
	v_mfma_f32_32x32x16_bf16 v[152:167], v[208:211], v[74:77], v[152:167]
	ds_read_b128 v[208:211], v122
	v_mfma_f32_32x32x16_bf16 v[16:31], v[214:217], v[244:247], v[16:31]
	ds_read_b128 v[244:247], v125 offset:8192
	v_mfma_f32_32x32x16_bf16 v[0:15], v[214:217], v[250:253], v[0:15]
	ds_read_b128 v[250:253], v125 offset:10240
	v_mfma_f32_32x32x16_bf16 v[168:183], v[214:217], v[68:71], v[168:183]
	ds_read_b128 v[68:71], v125 offset:49152
	v_mfma_f32_32x32x16_bf16 v[184:199], v[214:217], v[74:77], v[184:199]
	ds_read_b128 v[214:217], v122 offset:2048
	ds_read_b128 v[74:77], v125 offset:51200
	s_waitcnt lgkmcnt(6)
	v_mfma_f32_32x32x16_bf16 v[48:63], v[104:107], v[112:115], v[48:63]
	s_mov_b32 m0, s52
	v_lshl_add_u64 v[64:65], v[64:65], 0, s[44:45]
	global_load_lds_dwordx4 v[64:65], off
	v_mfma_f32_32x32x16_bf16 v[32:47], v[104:107], v[128:131], v[32:47]
	global_load_lds_dwordx4 v[64:65], off offset:1024
	v_mfma_f32_32x32x16_bf16 v[136:151], v[104:107], v[132:135], v[136:151]
	s_mov_b32 m0, s55
	v_lshl_add_u64 v[66:67], v[66:67], 0, s[44:45]
	global_load_lds_dwordx4 v[66:67], off
	v_mfma_f32_32x32x16_bf16 v[152:167], v[104:107], v[204:207], v[152:167]
	global_load_lds_dwordx4 v[66:67], off offset:1024
	v_mfma_f32_32x32x16_bf16 v[16:31], v[108:111], v[112:115], v[16:31]
	s_mov_b32 m0, s58
	v_lshl_add_u64 v[78:79], v[66:67], 0, s[72:73]
	global_load_lds_dwordx4 v[78:79], off
	v_mfma_f32_32x32x16_bf16 v[0:15], v[108:111], v[128:131], v[0:15]
	global_load_lds_dwordx4 v[78:79], off offset:1024
	v_mfma_f32_32x32x16_bf16 v[168:183], v[108:111], v[132:135], v[168:183]
	v_mfma_f32_32x32x16_bf16 v[184:199], v[108:111], v[204:207], v[184:199]
	s_waitcnt vmcnt(6)
	s_waitcnt lgkmcnt(0)
	s_barrier
	ds_read_b128 v[104:107], v116 offset:16384
	ds_read_b128 v[112:115], v119 offset:24576
	v_mfma_f32_32x32x16_bf16 v[48:63], v[208:211], v[244:247], v[48:63]
	ds_read_b128 v[128:131], v119 offset:26624
	ds_read_b128 v[132:135], v243 offset:40960
	v_mfma_f32_32x32x16_bf16 v[32:47], v[208:211], v[250:253], v[32:47]
	ds_read_b128 v[204:207], v243 offset:43008
	ds_read_b128 v[108:111], v116 offset:18432
	v_mfma_f32_32x32x16_bf16 v[136:151], v[208:211], v[68:71], v[136:151]
	v_mfma_f32_32x32x16_bf16 v[152:167], v[208:211], v[74:77], v[152:167]
	ds_read_b128 v[208:211], v122 offset:16384
	v_mfma_f32_32x32x16_bf16 v[16:31], v[214:217], v[244:247], v[16:31]
	ds_read_b128 v[244:247], v125 offset:24576
	v_mfma_f32_32x32x16_bf16 v[0:15], v[214:217], v[250:253], v[0:15]
	ds_read_b128 v[250:253], v125 offset:26624
	v_mfma_f32_32x32x16_bf16 v[168:183], v[214:217], v[68:71], v[168:183]
	ds_read_b128 v[68:71], v248 offset:40960
	v_mfma_f32_32x32x16_bf16 v[184:199], v[214:217], v[74:77], v[184:199]
	ds_read_b128 v[214:217], v122 offset:18432
	ds_read_b128 v[74:77], v248 offset:43008
	s_waitcnt lgkmcnt(6)
	v_mfma_f32_32x32x16_bf16 v[48:63], v[104:107], v[112:115], v[48:63]
	s_mov_b32 m0, s50
	v_lshl_add_u64 v[64:65], v[64:65], 0, s[44:45]
	global_load_lds_dwordx4 v[64:65], off
	v_mfma_f32_32x32x16_bf16 v[32:47], v[104:107], v[128:131], v[32:47]
	global_load_lds_dwordx4 v[64:65], off offset:1024
	v_mfma_f32_32x32x16_bf16 v[136:151], v[104:107], v[132:135], v[136:151]
	s_mov_b32 m0, s53
	v_lshl_add_u64 v[66:67], v[66:67], 0, s[44:45]
	global_load_lds_dwordx4 v[66:67], off
	v_mfma_f32_32x32x16_bf16 v[152:167], v[104:107], v[204:207], v[152:167]
	global_load_lds_dwordx4 v[66:67], off offset:1024
	v_mfma_f32_32x32x16_bf16 v[16:31], v[108:111], v[112:115], v[16:31]
	s_mov_b32 m0, s56
	v_lshl_add_u64 v[78:79], v[66:67], 0, s[72:73]
	global_load_lds_dwordx4 v[78:79], off
	v_mfma_f32_32x32x16_bf16 v[0:15], v[108:111], v[128:131], v[0:15]
	global_load_lds_dwordx4 v[78:79], off offset:1024
	v_mfma_f32_32x32x16_bf16 v[168:183], v[108:111], v[132:135], v[168:183]
	v_mfma_f32_32x32x16_bf16 v[184:199], v[108:111], v[204:207], v[184:199]
	s_waitcnt vmcnt(6)
	s_waitcnt lgkmcnt(0)
	s_barrier
	ds_read_b128 v[104:107], v116 offset:32768
	ds_read_b128 v[112:115], v119 offset:40960
	v_mfma_f32_32x32x16_bf16 v[48:63], v[208:211], v[244:247], v[48:63]
	ds_read_b128 v[128:131], v119 offset:43008
	ds_read_b128 v[132:135], v243 offset:57344
	v_mfma_f32_32x32x16_bf16 v[32:47], v[208:211], v[250:253], v[32:47]
	ds_read_b128 v[204:207], v243 offset:59392
	ds_read_b128 v[108:111], v116 offset:34816
	v_mfma_f32_32x32x16_bf16 v[136:151], v[208:211], v[68:71], v[136:151]
	v_mfma_f32_32x32x16_bf16 v[152:167], v[208:211], v[74:77], v[152:167]
	ds_read_b128 v[208:211], v122 offset:32768
	v_mfma_f32_32x32x16_bf16 v[16:31], v[214:217], v[244:247], v[16:31]
	ds_read_b128 v[244:247], v125 offset:40960
	v_mfma_f32_32x32x16_bf16 v[0:15], v[214:217], v[250:253], v[0:15]
	ds_read_b128 v[250:253], v125 offset:43008
	v_mfma_f32_32x32x16_bf16 v[168:183], v[214:217], v[68:71], v[168:183]
	ds_read_b128 v[68:71], v248 offset:57344
	v_mfma_f32_32x32x16_bf16 v[184:199], v[214:217], v[74:77], v[184:199]
	ds_read_b128 v[214:217], v122 offset:34816
	ds_read_b128 v[74:77], v248 offset:59392
	s_waitcnt lgkmcnt(6)
	v_mfma_f32_32x32x16_bf16 v[48:63], v[104:107], v[112:115], v[48:63]
	s_mov_b32 m0, s51
	v_lshl_add_u64 v[64:65], v[64:65], 0, s[44:45]
	global_load_lds_dwordx4 v[64:65], off
	v_mfma_f32_32x32x16_bf16 v[32:47], v[104:107], v[128:131], v[32:47]
	global_load_lds_dwordx4 v[64:65], off offset:1024
	v_mfma_f32_32x32x16_bf16 v[136:151], v[104:107], v[132:135], v[136:151]
	s_mov_b32 m0, s54
	v_lshl_add_u64 v[66:67], v[66:67], 0, s[44:45]
	global_load_lds_dwordx4 v[66:67], off
	v_mfma_f32_32x32x16_bf16 v[152:167], v[104:107], v[204:207], v[152:167]
	global_load_lds_dwordx4 v[66:67], off offset:1024
	v_mfma_f32_32x32x16_bf16 v[16:31], v[108:111], v[112:115], v[16:31]
	s_mov_b32 m0, s57
	v_lshl_add_u64 v[78:79], v[66:67], 0, s[72:73]
	global_load_lds_dwordx4 v[78:79], off
	v_mfma_f32_32x32x16_bf16 v[0:15], v[108:111], v[128:131], v[0:15]
	global_load_lds_dwordx4 v[78:79], off offset:1024
	v_mfma_f32_32x32x16_bf16 v[168:183], v[108:111], v[132:135], v[168:183]
	v_mfma_f32_32x32x16_bf16 v[184:199], v[108:111], v[204:207], v[184:199]
	s_waitcnt vmcnt(6)
	s_waitcnt lgkmcnt(0)
	s_barrier
	ds_read_b128 v[104:107], v116
	ds_read_b128 v[112:115], v119 offset:8192
	v_mfma_f32_32x32x16_bf16 v[48:63], v[208:211], v[244:247], v[48:63]
	ds_read_b128 v[128:131], v119 offset:10240
	ds_read_b128 v[132:135], v119 offset:49152
	v_mfma_f32_32x32x16_bf16 v[32:47], v[208:211], v[250:253], v[32:47]
	ds_read_b128 v[204:207], v119 offset:51200
	ds_read_b128 v[108:111], v116 offset:2048
	v_mfma_f32_32x32x16_bf16 v[136:151], v[208:211], v[68:71], v[136:151]
	v_mfma_f32_32x32x16_bf16 v[152:167], v[208:211], v[74:77], v[152:167]
	ds_read_b128 v[208:211], v122
	v_mfma_f32_32x32x16_bf16 v[16:31], v[214:217], v[244:247], v[16:31]
	ds_read_b128 v[244:247], v125 offset:8192
	v_mfma_f32_32x32x16_bf16 v[0:15], v[214:217], v[250:253], v[0:15]
	ds_read_b128 v[250:253], v125 offset:10240
	v_mfma_f32_32x32x16_bf16 v[168:183], v[214:217], v[68:71], v[168:183]
	ds_read_b128 v[68:71], v125 offset:49152
	v_mfma_f32_32x32x16_bf16 v[184:199], v[214:217], v[74:77], v[184:199]
	ds_read_b128 v[214:217], v122 offset:2048
	ds_read_b128 v[74:77], v125 offset:51200
	s_waitcnt lgkmcnt(6)
	v_mfma_f32_32x32x16_bf16 v[48:63], v[104:107], v[112:115], v[48:63]
	s_mov_b32 m0, s52
	v_lshl_add_u64 v[64:65], v[64:65], 0, s[44:45]
	global_load_lds_dwordx4 v[64:65], off
	v_mfma_f32_32x32x16_bf16 v[32:47], v[104:107], v[128:131], v[32:47]
	global_load_lds_dwordx4 v[64:65], off offset:1024
	v_mfma_f32_32x32x16_bf16 v[136:151], v[104:107], v[132:135], v[136:151]
	s_mov_b32 m0, s55
	v_lshl_add_u64 v[66:67], v[66:67], 0, s[44:45]
	global_load_lds_dwordx4 v[66:67], off
	v_mfma_f32_32x32x16_bf16 v[152:167], v[104:107], v[204:207], v[152:167]
	global_load_lds_dwordx4 v[66:67], off offset:1024
	v_mfma_f32_32x32x16_bf16 v[16:31], v[108:111], v[112:115], v[16:31]
	s_mov_b32 m0, s58
	v_lshl_add_u64 v[78:79], v[66:67], 0, s[72:73]
	global_load_lds_dwordx4 v[78:79], off
	v_mfma_f32_32x32x16_bf16 v[0:15], v[108:111], v[128:131], v[0:15]
	global_load_lds_dwordx4 v[78:79], off offset:1024
	v_mfma_f32_32x32x16_bf16 v[168:183], v[108:111], v[132:135], v[168:183]
	v_mfma_f32_32x32x16_bf16 v[184:199], v[108:111], v[204:207], v[184:199]
	s_waitcnt vmcnt(6)
	s_waitcnt lgkmcnt(0)
	s_barrier
	ds_read_b128 v[104:107], v116 offset:16384
	ds_read_b128 v[112:115], v119 offset:24576
	v_mfma_f32_32x32x16_bf16 v[48:63], v[208:211], v[244:247], v[48:63]
	ds_read_b128 v[128:131], v119 offset:26624
	ds_read_b128 v[132:135], v243 offset:40960
	v_mfma_f32_32x32x16_bf16 v[32:47], v[208:211], v[250:253], v[32:47]
	ds_read_b128 v[204:207], v243 offset:43008
	ds_read_b128 v[108:111], v116 offset:18432
	v_mfma_f32_32x32x16_bf16 v[136:151], v[208:211], v[68:71], v[136:151]
	v_mfma_f32_32x32x16_bf16 v[152:167], v[208:211], v[74:77], v[152:167]
	ds_read_b128 v[208:211], v122 offset:16384
	v_mfma_f32_32x32x16_bf16 v[16:31], v[214:217], v[244:247], v[16:31]
	ds_read_b128 v[244:247], v125 offset:24576
	v_mfma_f32_32x32x16_bf16 v[0:15], v[214:217], v[250:253], v[0:15]
	ds_read_b128 v[250:253], v125 offset:26624
	v_mfma_f32_32x32x16_bf16 v[168:183], v[214:217], v[68:71], v[168:183]
	ds_read_b128 v[68:71], v248 offset:40960
	v_mfma_f32_32x32x16_bf16 v[184:199], v[214:217], v[74:77], v[184:199]
	ds_read_b128 v[214:217], v122 offset:18432
	ds_read_b128 v[74:77], v248 offset:43008
	s_waitcnt lgkmcnt(6)
	v_mfma_f32_32x32x16_bf16 v[48:63], v[104:107], v[112:115], v[48:63]
	s_mov_b32 m0, s50
	v_lshl_add_u64 v[64:65], v[64:65], 0, s[44:45]
	global_load_lds_dwordx4 v[64:65], off
	v_mfma_f32_32x32x16_bf16 v[32:47], v[104:107], v[128:131], v[32:47]
	global_load_lds_dwordx4 v[64:65], off offset:1024
	v_mfma_f32_32x32x16_bf16 v[136:151], v[104:107], v[132:135], v[136:151]
	s_mov_b32 m0, s53
	v_lshl_add_u64 v[66:67], v[66:67], 0, s[44:45]
	global_load_lds_dwordx4 v[66:67], off
	v_mfma_f32_32x32x16_bf16 v[152:167], v[104:107], v[204:207], v[152:167]
	global_load_lds_dwordx4 v[66:67], off offset:1024
	v_mfma_f32_32x32x16_bf16 v[16:31], v[108:111], v[112:115], v[16:31]
	s_mov_b32 m0, s56
	v_lshl_add_u64 v[78:79], v[66:67], 0, s[72:73]
	global_load_lds_dwordx4 v[78:79], off
	v_mfma_f32_32x32x16_bf16 v[0:15], v[108:111], v[128:131], v[0:15]
	global_load_lds_dwordx4 v[78:79], off offset:1024
	v_mfma_f32_32x32x16_bf16 v[168:183], v[108:111], v[132:135], v[168:183]
	v_mfma_f32_32x32x16_bf16 v[184:199], v[108:111], v[204:207], v[184:199]
	s_waitcnt vmcnt(6)
	s_waitcnt lgkmcnt(0)
	s_barrier
	ds_read_b128 v[104:107], v116 offset:32768
	ds_read_b128 v[112:115], v119 offset:40960
	v_mfma_f32_32x32x16_bf16 v[48:63], v[208:211], v[244:247], v[48:63]
	ds_read_b128 v[128:131], v119 offset:43008
	ds_read_b128 v[132:135], v243 offset:57344
	v_mfma_f32_32x32x16_bf16 v[32:47], v[208:211], v[250:253], v[32:47]
	ds_read_b128 v[204:207], v243 offset:59392
	ds_read_b128 v[108:111], v116 offset:34816
	v_mfma_f32_32x32x16_bf16 v[136:151], v[208:211], v[68:71], v[136:151]
	v_mfma_f32_32x32x16_bf16 v[152:167], v[208:211], v[74:77], v[152:167]
	ds_read_b128 v[208:211], v122 offset:32768
	v_mfma_f32_32x32x16_bf16 v[16:31], v[214:217], v[244:247], v[16:31]
	ds_read_b128 v[244:247], v125 offset:40960
	v_mfma_f32_32x32x16_bf16 v[0:15], v[214:217], v[250:253], v[0:15]
	ds_read_b128 v[250:253], v125 offset:43008
	v_mfma_f32_32x32x16_bf16 v[168:183], v[214:217], v[68:71], v[168:183]
	ds_read_b128 v[68:71], v248 offset:57344
	v_mfma_f32_32x32x16_bf16 v[184:199], v[214:217], v[74:77], v[184:199]
	ds_read_b128 v[214:217], v122 offset:34816
	ds_read_b128 v[74:77], v248 offset:59392
	s_waitcnt lgkmcnt(6)
	v_mfma_f32_32x32x16_bf16 v[48:63], v[104:107], v[112:115], v[48:63]
	s_mov_b32 m0, s51
	v_lshl_add_u64 v[64:65], v[64:65], 0, s[44:45]
	global_load_lds_dwordx4 v[64:65], off
	v_mfma_f32_32x32x16_bf16 v[32:47], v[104:107], v[128:131], v[32:47]
	global_load_lds_dwordx4 v[64:65], off offset:1024
	v_mfma_f32_32x32x16_bf16 v[136:151], v[104:107], v[132:135], v[136:151]
	s_mov_b32 m0, s54
	v_lshl_add_u64 v[66:67], v[66:67], 0, s[44:45]
	global_load_lds_dwordx4 v[66:67], off
	v_mfma_f32_32x32x16_bf16 v[152:167], v[104:107], v[204:207], v[152:167]
	global_load_lds_dwordx4 v[66:67], off offset:1024
	v_mfma_f32_32x32x16_bf16 v[16:31], v[108:111], v[112:115], v[16:31]
	s_mov_b32 m0, s57
	v_lshl_add_u64 v[78:79], v[66:67], 0, s[72:73]
	global_load_lds_dwordx4 v[78:79], off
	v_mfma_f32_32x32x16_bf16 v[0:15], v[108:111], v[128:131], v[0:15]
	global_load_lds_dwordx4 v[78:79], off offset:1024
	v_mfma_f32_32x32x16_bf16 v[168:183], v[108:111], v[132:135], v[168:183]
	v_mfma_f32_32x32x16_bf16 v[184:199], v[108:111], v[204:207], v[184:199]
	s_waitcnt vmcnt(6)
	s_waitcnt lgkmcnt(0)
	s_barrier
	ds_read_b128 v[104:107], v116
	ds_read_b128 v[112:115], v119 offset:8192
	v_mfma_f32_32x32x16_bf16 v[48:63], v[208:211], v[244:247], v[48:63]
	ds_read_b128 v[128:131], v119 offset:10240
	ds_read_b128 v[132:135], v119 offset:49152
	v_mfma_f32_32x32x16_bf16 v[32:47], v[208:211], v[250:253], v[32:47]
	ds_read_b128 v[204:207], v119 offset:51200
	ds_read_b128 v[108:111], v116 offset:2048
	v_mfma_f32_32x32x16_bf16 v[136:151], v[208:211], v[68:71], v[136:151]
	v_mfma_f32_32x32x16_bf16 v[152:167], v[208:211], v[74:77], v[152:167]
	ds_read_b128 v[208:211], v122
	v_mfma_f32_32x32x16_bf16 v[16:31], v[214:217], v[244:247], v[16:31]
	ds_read_b128 v[244:247], v125 offset:8192
	v_mfma_f32_32x32x16_bf16 v[0:15], v[214:217], v[250:253], v[0:15]
	ds_read_b128 v[250:253], v125 offset:10240
	v_mfma_f32_32x32x16_bf16 v[168:183], v[214:217], v[68:71], v[168:183]
	ds_read_b128 v[68:71], v125 offset:49152
	v_mfma_f32_32x32x16_bf16 v[184:199], v[214:217], v[74:77], v[184:199]
	ds_read_b128 v[214:217], v122 offset:2048
	ds_read_b128 v[74:77], v125 offset:51200
	s_waitcnt lgkmcnt(6)
	v_mfma_f32_32x32x16_bf16 v[48:63], v[104:107], v[112:115], v[48:63]
	s_mov_b32 m0, s52
	v_lshl_add_u64 v[64:65], v[64:65], 0, s[44:45]
	global_load_lds_dwordx4 v[64:65], off
	v_mfma_f32_32x32x16_bf16 v[32:47], v[104:107], v[128:131], v[32:47]
	global_load_lds_dwordx4 v[64:65], off offset:1024
	v_mfma_f32_32x32x16_bf16 v[136:151], v[104:107], v[132:135], v[136:151]
	s_mov_b32 m0, s55
	v_lshl_add_u64 v[66:67], v[66:67], 0, s[44:45]
	global_load_lds_dwordx4 v[66:67], off
	v_mfma_f32_32x32x16_bf16 v[152:167], v[104:107], v[204:207], v[152:167]
	global_load_lds_dwordx4 v[66:67], off offset:1024
	v_mfma_f32_32x32x16_bf16 v[16:31], v[108:111], v[112:115], v[16:31]
	s_mov_b32 m0, s58
	v_lshl_add_u64 v[78:79], v[66:67], 0, s[72:73]
	global_load_lds_dwordx4 v[78:79], off
	v_mfma_f32_32x32x16_bf16 v[0:15], v[108:111], v[128:131], v[0:15]
	global_load_lds_dwordx4 v[78:79], off offset:1024
	v_mfma_f32_32x32x16_bf16 v[168:183], v[108:111], v[132:135], v[168:183]
	v_mfma_f32_32x32x16_bf16 v[184:199], v[108:111], v[204:207], v[184:199]
	s_waitcnt vmcnt(6)
	s_waitcnt lgkmcnt(0)
	s_barrier
	ds_read_b128 v[104:107], v116 offset:16384
	ds_read_b128 v[112:115], v119 offset:24576
	v_mfma_f32_32x32x16_bf16 v[48:63], v[208:211], v[244:247], v[48:63]
	ds_read_b128 v[128:131], v119 offset:26624
	ds_read_b128 v[132:135], v243 offset:40960
	v_mfma_f32_32x32x16_bf16 v[32:47], v[208:211], v[250:253], v[32:47]
	ds_read_b128 v[204:207], v243 offset:43008
	ds_read_b128 v[108:111], v116 offset:18432
	v_mfma_f32_32x32x16_bf16 v[136:151], v[208:211], v[68:71], v[136:151]
	v_mfma_f32_32x32x16_bf16 v[152:167], v[208:211], v[74:77], v[152:167]
	ds_read_b128 v[208:211], v122 offset:16384
	v_mfma_f32_32x32x16_bf16 v[16:31], v[214:217], v[244:247], v[16:31]
	ds_read_b128 v[244:247], v125 offset:24576
	v_mfma_f32_32x32x16_bf16 v[0:15], v[214:217], v[250:253], v[0:15]
	ds_read_b128 v[250:253], v125 offset:26624
	v_mfma_f32_32x32x16_bf16 v[168:183], v[214:217], v[68:71], v[168:183]
	ds_read_b128 v[68:71], v248 offset:40960
	v_mfma_f32_32x32x16_bf16 v[184:199], v[214:217], v[74:77], v[184:199]
	ds_read_b128 v[214:217], v122 offset:18432
	ds_read_b128 v[74:77], v248 offset:43008
	s_waitcnt lgkmcnt(6)
	v_mfma_f32_32x32x16_bf16 v[48:63], v[104:107], v[112:115], v[48:63]
	s_mov_b32 m0, s50
	v_lshl_add_u64 v[64:65], v[64:65], 0, s[44:45]
	global_load_lds_dwordx4 v[64:65], off
	v_mfma_f32_32x32x16_bf16 v[32:47], v[104:107], v[128:131], v[32:47]
	global_load_lds_dwordx4 v[64:65], off offset:1024
	v_mfma_f32_32x32x16_bf16 v[136:151], v[104:107], v[132:135], v[136:151]
	s_mov_b32 m0, s53
	v_lshl_add_u64 v[66:67], v[66:67], 0, s[44:45]
	global_load_lds_dwordx4 v[66:67], off
	v_mfma_f32_32x32x16_bf16 v[152:167], v[104:107], v[204:207], v[152:167]
	global_load_lds_dwordx4 v[66:67], off offset:1024
	v_mfma_f32_32x32x16_bf16 v[16:31], v[108:111], v[112:115], v[16:31]
	s_mov_b32 m0, s56
	v_lshl_add_u64 v[78:79], v[66:67], 0, s[72:73]
	global_load_lds_dwordx4 v[78:79], off
	v_mfma_f32_32x32x16_bf16 v[0:15], v[108:111], v[128:131], v[0:15]
	global_load_lds_dwordx4 v[78:79], off offset:1024
	v_mfma_f32_32x32x16_bf16 v[168:183], v[108:111], v[132:135], v[168:183]
	v_mfma_f32_32x32x16_bf16 v[184:199], v[108:111], v[204:207], v[184:199]
	s_waitcnt vmcnt(6)
	s_waitcnt lgkmcnt(0)
	s_barrier
	ds_read_b128 v[104:107], v116 offset:32768
	ds_read_b128 v[112:115], v119 offset:40960
	v_mfma_f32_32x32x16_bf16 v[48:63], v[208:211], v[244:247], v[48:63]
	ds_read_b128 v[128:131], v119 offset:43008
	ds_read_b128 v[132:135], v243 offset:57344
	v_mfma_f32_32x32x16_bf16 v[32:47], v[208:211], v[250:253], v[32:47]
	ds_read_b128 v[204:207], v243 offset:59392
	ds_read_b128 v[108:111], v116 offset:34816
	v_mfma_f32_32x32x16_bf16 v[136:151], v[208:211], v[68:71], v[136:151]
	v_mfma_f32_32x32x16_bf16 v[152:167], v[208:211], v[74:77], v[152:167]
	ds_read_b128 v[208:211], v122 offset:32768
	v_mfma_f32_32x32x16_bf16 v[16:31], v[214:217], v[244:247], v[16:31]
	ds_read_b128 v[244:247], v125 offset:40960
	v_mfma_f32_32x32x16_bf16 v[0:15], v[214:217], v[250:253], v[0:15]
	ds_read_b128 v[250:253], v125 offset:43008
	v_mfma_f32_32x32x16_bf16 v[168:183], v[214:217], v[68:71], v[168:183]
	ds_read_b128 v[68:71], v248 offset:57344
	v_mfma_f32_32x32x16_bf16 v[184:199], v[214:217], v[74:77], v[184:199]
	ds_read_b128 v[214:217], v122 offset:34816
	ds_read_b128 v[74:77], v248 offset:59392
	s_waitcnt lgkmcnt(6)
	v_mfma_f32_32x32x16_bf16 v[48:63], v[104:107], v[112:115], v[48:63]
	s_mov_b32 m0, s51
	v_lshl_add_u64 v[64:65], v[64:65], 0, s[44:45]
	global_load_lds_dwordx4 v[64:65], off
	v_mfma_f32_32x32x16_bf16 v[32:47], v[104:107], v[128:131], v[32:47]
	global_load_lds_dwordx4 v[64:65], off offset:1024
	v_mfma_f32_32x32x16_bf16 v[136:151], v[104:107], v[132:135], v[136:151]
	s_mov_b32 m0, s54
	v_lshl_add_u64 v[66:67], v[66:67], 0, s[44:45]
	global_load_lds_dwordx4 v[66:67], off
	v_mfma_f32_32x32x16_bf16 v[152:167], v[104:107], v[204:207], v[152:167]
	global_load_lds_dwordx4 v[66:67], off offset:1024
	v_mfma_f32_32x32x16_bf16 v[16:31], v[108:111], v[112:115], v[16:31]
	s_mov_b32 m0, s57
	v_lshl_add_u64 v[78:79], v[66:67], 0, s[72:73]
	global_load_lds_dwordx4 v[78:79], off
	v_mfma_f32_32x32x16_bf16 v[0:15], v[108:111], v[128:131], v[0:15]
	global_load_lds_dwordx4 v[78:79], off offset:1024
	v_mfma_f32_32x32x16_bf16 v[168:183], v[108:111], v[132:135], v[168:183]
	v_mfma_f32_32x32x16_bf16 v[184:199], v[108:111], v[204:207], v[184:199]
	s_waitcnt vmcnt(6)
	s_waitcnt lgkmcnt(0)
	s_barrier
	ds_read_b128 v[104:107], v116
	ds_read_b128 v[112:115], v119 offset:8192
	v_mfma_f32_32x32x16_bf16 v[48:63], v[208:211], v[244:247], v[48:63]
	ds_read_b128 v[128:131], v119 offset:10240
	ds_read_b128 v[132:135], v119 offset:49152
	v_mfma_f32_32x32x16_bf16 v[32:47], v[208:211], v[250:253], v[32:47]
	ds_read_b128 v[204:207], v119 offset:51200
	ds_read_b128 v[108:111], v116 offset:2048
	v_mfma_f32_32x32x16_bf16 v[136:151], v[208:211], v[68:71], v[136:151]
	v_mfma_f32_32x32x16_bf16 v[152:167], v[208:211], v[74:77], v[152:167]
	ds_read_b128 v[208:211], v122
	v_mfma_f32_32x32x16_bf16 v[16:31], v[214:217], v[244:247], v[16:31]
	ds_read_b128 v[244:247], v125 offset:8192
	v_mfma_f32_32x32x16_bf16 v[0:15], v[214:217], v[250:253], v[0:15]
	ds_read_b128 v[250:253], v125 offset:10240
	v_mfma_f32_32x32x16_bf16 v[168:183], v[214:217], v[68:71], v[168:183]
	ds_read_b128 v[68:71], v125 offset:49152
	v_mfma_f32_32x32x16_bf16 v[184:199], v[214:217], v[74:77], v[184:199]
	ds_read_b128 v[214:217], v122 offset:2048
	ds_read_b128 v[74:77], v125 offset:51200
	s_waitcnt lgkmcnt(6)
	v_mfma_f32_32x32x16_bf16 v[48:63], v[104:107], v[112:115], v[48:63]
	s_mov_b32 m0, s52
	v_lshl_add_u64 v[64:65], v[64:65], 0, s[44:45]
	global_load_lds_dwordx4 v[64:65], off
	v_mfma_f32_32x32x16_bf16 v[32:47], v[104:107], v[128:131], v[32:47]
	global_load_lds_dwordx4 v[64:65], off offset:1024
	v_mfma_f32_32x32x16_bf16 v[136:151], v[104:107], v[132:135], v[136:151]
	s_mov_b32 m0, s55
	v_lshl_add_u64 v[66:67], v[66:67], 0, s[44:45]
	global_load_lds_dwordx4 v[66:67], off
	v_mfma_f32_32x32x16_bf16 v[152:167], v[104:107], v[204:207], v[152:167]
	global_load_lds_dwordx4 v[66:67], off offset:1024
	v_mfma_f32_32x32x16_bf16 v[16:31], v[108:111], v[112:115], v[16:31]
	s_mov_b32 m0, s58
	v_lshl_add_u64 v[78:79], v[66:67], 0, s[72:73]
	global_load_lds_dwordx4 v[78:79], off
	v_mfma_f32_32x32x16_bf16 v[0:15], v[108:111], v[128:131], v[0:15]
	global_load_lds_dwordx4 v[78:79], off offset:1024
	v_mfma_f32_32x32x16_bf16 v[168:183], v[108:111], v[132:135], v[168:183]
	v_mfma_f32_32x32x16_bf16 v[184:199], v[108:111], v[204:207], v[184:199]
	s_waitcnt vmcnt(6)
	s_waitcnt lgkmcnt(0)
	s_barrier
	ds_read_b128 v[104:107], v116 offset:16384
	ds_read_b128 v[112:115], v119 offset:24576
	v_mfma_f32_32x32x16_bf16 v[48:63], v[208:211], v[244:247], v[48:63]
	ds_read_b128 v[128:131], v119 offset:26624
	ds_read_b128 v[132:135], v243 offset:40960
	v_mfma_f32_32x32x16_bf16 v[32:47], v[208:211], v[250:253], v[32:47]
	ds_read_b128 v[204:207], v243 offset:43008
	ds_read_b128 v[108:111], v116 offset:18432
	v_mfma_f32_32x32x16_bf16 v[136:151], v[208:211], v[68:71], v[136:151]
	v_mfma_f32_32x32x16_bf16 v[152:167], v[208:211], v[74:77], v[152:167]
	ds_read_b128 v[208:211], v122 offset:16384
	v_mfma_f32_32x32x16_bf16 v[16:31], v[214:217], v[244:247], v[16:31]
	ds_read_b128 v[244:247], v125 offset:24576
	v_mfma_f32_32x32x16_bf16 v[0:15], v[214:217], v[250:253], v[0:15]
	ds_read_b128 v[250:253], v125 offset:26624
	v_mfma_f32_32x32x16_bf16 v[168:183], v[214:217], v[68:71], v[168:183]
	ds_read_b128 v[68:71], v248 offset:40960
	v_mfma_f32_32x32x16_bf16 v[184:199], v[214:217], v[74:77], v[184:199]
	ds_read_b128 v[214:217], v122 offset:18432
	ds_read_b128 v[74:77], v248 offset:43008
	s_waitcnt lgkmcnt(6)
	v_mfma_f32_32x32x16_bf16 v[48:63], v[104:107], v[112:115], v[48:63]
	s_mov_b32 m0, s50
	v_lshl_add_u64 v[64:65], v[64:65], 0, s[44:45]
	global_load_lds_dwordx4 v[64:65], off
	v_mfma_f32_32x32x16_bf16 v[32:47], v[104:107], v[128:131], v[32:47]
	global_load_lds_dwordx4 v[64:65], off offset:1024
	v_mfma_f32_32x32x16_bf16 v[136:151], v[104:107], v[132:135], v[136:151]
	s_mov_b32 m0, s53
	v_lshl_add_u64 v[66:67], v[66:67], 0, s[44:45]
	global_load_lds_dwordx4 v[66:67], off
	v_mfma_f32_32x32x16_bf16 v[152:167], v[104:107], v[204:207], v[152:167]
	global_load_lds_dwordx4 v[66:67], off offset:1024
	v_mfma_f32_32x32x16_bf16 v[16:31], v[108:111], v[112:115], v[16:31]
	s_mov_b32 m0, s56
	v_lshl_add_u64 v[78:79], v[66:67], 0, s[72:73]
	global_load_lds_dwordx4 v[78:79], off
	v_mfma_f32_32x32x16_bf16 v[0:15], v[108:111], v[128:131], v[0:15]
	global_load_lds_dwordx4 v[78:79], off offset:1024
	v_mfma_f32_32x32x16_bf16 v[168:183], v[108:111], v[132:135], v[168:183]
	v_mfma_f32_32x32x16_bf16 v[184:199], v[108:111], v[204:207], v[184:199]
	s_waitcnt vmcnt(6)
	s_waitcnt lgkmcnt(0)
	s_barrier
	ds_read_b128 v[104:107], v116 offset:32768
	ds_read_b128 v[112:115], v119 offset:40960
	v_mfma_f32_32x32x16_bf16 v[48:63], v[208:211], v[244:247], v[48:63]
	ds_read_b128 v[128:131], v119 offset:43008
	ds_read_b128 v[132:135], v243 offset:57344
	v_mfma_f32_32x32x16_bf16 v[32:47], v[208:211], v[250:253], v[32:47]
	ds_read_b128 v[204:207], v243 offset:59392
	ds_read_b128 v[108:111], v116 offset:34816
	v_mfma_f32_32x32x16_bf16 v[136:151], v[208:211], v[68:71], v[136:151]
	v_mfma_f32_32x32x16_bf16 v[152:167], v[208:211], v[74:77], v[152:167]
	ds_read_b128 v[208:211], v122 offset:32768
	v_mfma_f32_32x32x16_bf16 v[16:31], v[214:217], v[244:247], v[16:31]
	ds_read_b128 v[244:247], v125 offset:40960
	v_mfma_f32_32x32x16_bf16 v[0:15], v[214:217], v[250:253], v[0:15]
	ds_read_b128 v[250:253], v125 offset:43008
	v_mfma_f32_32x32x16_bf16 v[168:183], v[214:217], v[68:71], v[168:183]
	ds_read_b128 v[68:71], v248 offset:57344
	v_mfma_f32_32x32x16_bf16 v[184:199], v[214:217], v[74:77], v[184:199]
	ds_read_b128 v[214:217], v122 offset:34816
	ds_read_b128 v[74:77], v248 offset:59392
	s_waitcnt lgkmcnt(6)
	v_mfma_f32_32x32x16_bf16 v[48:63], v[104:107], v[112:115], v[48:63]
	s_mov_b32 m0, s51
	v_lshl_add_u64 v[64:65], v[64:65], 0, s[44:45]
	global_load_lds_dwordx4 v[64:65], off
	v_mfma_f32_32x32x16_bf16 v[32:47], v[104:107], v[128:131], v[32:47]
	global_load_lds_dwordx4 v[64:65], off offset:1024
	v_mfma_f32_32x32x16_bf16 v[136:151], v[104:107], v[132:135], v[136:151]
	s_mov_b32 m0, s54
	v_lshl_add_u64 v[66:67], v[66:67], 0, s[44:45]
	global_load_lds_dwordx4 v[66:67], off
	v_mfma_f32_32x32x16_bf16 v[152:167], v[104:107], v[204:207], v[152:167]
	global_load_lds_dwordx4 v[66:67], off offset:1024
	v_mfma_f32_32x32x16_bf16 v[16:31], v[108:111], v[112:115], v[16:31]
	s_mov_b32 m0, s57
	v_lshl_add_u64 v[78:79], v[66:67], 0, s[72:73]
	global_load_lds_dwordx4 v[78:79], off
	v_mfma_f32_32x32x16_bf16 v[0:15], v[108:111], v[128:131], v[0:15]
	global_load_lds_dwordx4 v[78:79], off offset:1024
	v_mfma_f32_32x32x16_bf16 v[168:183], v[108:111], v[132:135], v[168:183]
	v_mfma_f32_32x32x16_bf16 v[184:199], v[108:111], v[204:207], v[184:199]
	s_waitcnt vmcnt(6)
	s_waitcnt lgkmcnt(0)
	s_barrier
	ds_read_b128 v[104:107], v116
	ds_read_b128 v[112:115], v119 offset:8192
	v_mfma_f32_32x32x16_bf16 v[48:63], v[208:211], v[244:247], v[48:63]
	ds_read_b128 v[128:131], v119 offset:10240
	ds_read_b128 v[132:135], v119 offset:49152
	v_mfma_f32_32x32x16_bf16 v[32:47], v[208:211], v[250:253], v[32:47]
	ds_read_b128 v[204:207], v119 offset:51200
	ds_read_b128 v[108:111], v116 offset:2048
	v_mfma_f32_32x32x16_bf16 v[136:151], v[208:211], v[68:71], v[136:151]
	v_mfma_f32_32x32x16_bf16 v[152:167], v[208:211], v[74:77], v[152:167]
	ds_read_b128 v[208:211], v122
	v_mfma_f32_32x32x16_bf16 v[16:31], v[214:217], v[244:247], v[16:31]
	ds_read_b128 v[244:247], v125 offset:8192
	v_mfma_f32_32x32x16_bf16 v[0:15], v[214:217], v[250:253], v[0:15]
	ds_read_b128 v[250:253], v125 offset:10240
	v_mfma_f32_32x32x16_bf16 v[168:183], v[214:217], v[68:71], v[168:183]
	ds_read_b128 v[68:71], v125 offset:49152
	v_mfma_f32_32x32x16_bf16 v[184:199], v[214:217], v[74:77], v[184:199]
	ds_read_b128 v[214:217], v122 offset:2048
	ds_read_b128 v[74:77], v125 offset:51200
	s_waitcnt lgkmcnt(6)
	v_mfma_f32_32x32x16_bf16 v[48:63], v[104:107], v[112:115], v[48:63]
	s_mov_b32 m0, s52
	v_lshl_add_u64 v[64:65], v[64:65], 0, s[44:45]
	global_load_lds_dwordx4 v[64:65], off
	v_mfma_f32_32x32x16_bf16 v[32:47], v[104:107], v[128:131], v[32:47]
	global_load_lds_dwordx4 v[64:65], off offset:1024
	v_mfma_f32_32x32x16_bf16 v[136:151], v[104:107], v[132:135], v[136:151]
	s_mov_b32 m0, s55
	v_lshl_add_u64 v[66:67], v[66:67], 0, s[44:45]
	global_load_lds_dwordx4 v[66:67], off
	v_mfma_f32_32x32x16_bf16 v[152:167], v[104:107], v[204:207], v[152:167]
	global_load_lds_dwordx4 v[66:67], off offset:1024
	v_mfma_f32_32x32x16_bf16 v[16:31], v[108:111], v[112:115], v[16:31]
	s_mov_b32 m0, s58
	v_lshl_add_u64 v[78:79], v[66:67], 0, s[72:73]
	global_load_lds_dwordx4 v[78:79], off
	v_mfma_f32_32x32x16_bf16 v[0:15], v[108:111], v[128:131], v[0:15]
	global_load_lds_dwordx4 v[78:79], off offset:1024
	v_mfma_f32_32x32x16_bf16 v[168:183], v[108:111], v[132:135], v[168:183]
	v_mfma_f32_32x32x16_bf16 v[184:199], v[108:111], v[204:207], v[184:199]
	s_waitcnt vmcnt(6)
	s_waitcnt lgkmcnt(0)
	s_barrier
	ds_read_b128 v[104:107], v116 offset:16384
	ds_read_b128 v[112:115], v119 offset:24576
	v_mfma_f32_32x32x16_bf16 v[48:63], v[208:211], v[244:247], v[48:63]
	ds_read_b128 v[128:131], v119 offset:26624
	ds_read_b128 v[132:135], v243 offset:40960
	v_mfma_f32_32x32x16_bf16 v[32:47], v[208:211], v[250:253], v[32:47]
	ds_read_b128 v[204:207], v243 offset:43008
	ds_read_b128 v[108:111], v116 offset:18432
	v_mfma_f32_32x32x16_bf16 v[136:151], v[208:211], v[68:71], v[136:151]
	v_mfma_f32_32x32x16_bf16 v[152:167], v[208:211], v[74:77], v[152:167]
	ds_read_b128 v[208:211], v122 offset:16384
	v_mfma_f32_32x32x16_bf16 v[16:31], v[214:217], v[244:247], v[16:31]
	ds_read_b128 v[244:247], v125 offset:24576
	v_mfma_f32_32x32x16_bf16 v[0:15], v[214:217], v[250:253], v[0:15]
	ds_read_b128 v[250:253], v125 offset:26624
	v_mfma_f32_32x32x16_bf16 v[168:183], v[214:217], v[68:71], v[168:183]
	ds_read_b128 v[68:71], v248 offset:40960
	v_mfma_f32_32x32x16_bf16 v[184:199], v[214:217], v[74:77], v[184:199]
	ds_read_b128 v[214:217], v122 offset:18432
	ds_read_b128 v[74:77], v248 offset:43008
	s_waitcnt lgkmcnt(6)
	v_mfma_f32_32x32x16_bf16 v[48:63], v[104:107], v[112:115], v[48:63]
	s_mov_b32 m0, s50
	v_lshl_add_u64 v[64:65], v[64:65], 0, s[44:45]
	global_load_lds_dwordx4 v[64:65], off
	v_mfma_f32_32x32x16_bf16 v[32:47], v[104:107], v[128:131], v[32:47]
	global_load_lds_dwordx4 v[64:65], off offset:1024
	v_mfma_f32_32x32x16_bf16 v[136:151], v[104:107], v[132:135], v[136:151]
	s_mov_b32 m0, s53
	v_lshl_add_u64 v[66:67], v[66:67], 0, s[44:45]
	global_load_lds_dwordx4 v[66:67], off
	v_mfma_f32_32x32x16_bf16 v[152:167], v[104:107], v[204:207], v[152:167]
	global_load_lds_dwordx4 v[66:67], off offset:1024
	v_mfma_f32_32x32x16_bf16 v[16:31], v[108:111], v[112:115], v[16:31]
	s_mov_b32 m0, s56
	v_lshl_add_u64 v[78:79], v[66:67], 0, s[72:73]
	global_load_lds_dwordx4 v[78:79], off
	v_mfma_f32_32x32x16_bf16 v[0:15], v[108:111], v[128:131], v[0:15]
	global_load_lds_dwordx4 v[78:79], off offset:1024
	v_mfma_f32_32x32x16_bf16 v[168:183], v[108:111], v[132:135], v[168:183]
	v_mfma_f32_32x32x16_bf16 v[184:199], v[108:111], v[204:207], v[184:199]
	s_waitcnt vmcnt(6)
	s_waitcnt lgkmcnt(0)
	s_barrier
	ds_read_b128 v[104:107], v116 offset:32768
	ds_read_b128 v[112:115], v119 offset:40960
	v_mfma_f32_32x32x16_bf16 v[48:63], v[208:211], v[244:247], v[48:63]
	ds_read_b128 v[128:131], v119 offset:43008
	ds_read_b128 v[132:135], v243 offset:57344
	v_mfma_f32_32x32x16_bf16 v[32:47], v[208:211], v[250:253], v[32:47]
	ds_read_b128 v[204:207], v243 offset:59392
	ds_read_b128 v[108:111], v116 offset:34816
	v_mfma_f32_32x32x16_bf16 v[136:151], v[208:211], v[68:71], v[136:151]
	v_mfma_f32_32x32x16_bf16 v[152:167], v[208:211], v[74:77], v[152:167]
	ds_read_b128 v[208:211], v122 offset:32768
	v_mfma_f32_32x32x16_bf16 v[16:31], v[214:217], v[244:247], v[16:31]
	ds_read_b128 v[244:247], v125 offset:40960
	v_mfma_f32_32x32x16_bf16 v[0:15], v[214:217], v[250:253], v[0:15]
	ds_read_b128 v[250:253], v125 offset:43008
	v_mfma_f32_32x32x16_bf16 v[168:183], v[214:217], v[68:71], v[168:183]
	ds_read_b128 v[68:71], v248 offset:57344
	v_mfma_f32_32x32x16_bf16 v[184:199], v[214:217], v[74:77], v[184:199]
	ds_read_b128 v[214:217], v122 offset:34816
	ds_read_b128 v[74:77], v248 offset:59392
	s_waitcnt lgkmcnt(6)
	v_mfma_f32_32x32x16_bf16 v[48:63], v[104:107], v[112:115], v[48:63]
	s_mov_b32 m0, s51
	v_lshl_add_u64 v[64:65], v[64:65], 0, s[44:45]
	global_load_lds_dwordx4 v[64:65], off
	v_mfma_f32_32x32x16_bf16 v[32:47], v[104:107], v[128:131], v[32:47]
	global_load_lds_dwordx4 v[64:65], off offset:1024
	v_mfma_f32_32x32x16_bf16 v[136:151], v[104:107], v[132:135], v[136:151]
	s_mov_b32 m0, s54
	v_lshl_add_u64 v[66:67], v[66:67], 0, s[44:45]
	global_load_lds_dwordx4 v[66:67], off
	v_mfma_f32_32x32x16_bf16 v[152:167], v[104:107], v[204:207], v[152:167]
	global_load_lds_dwordx4 v[66:67], off offset:1024
	v_mfma_f32_32x32x16_bf16 v[16:31], v[108:111], v[112:115], v[16:31]
	s_mov_b32 m0, s57
	v_lshl_add_u64 v[78:79], v[66:67], 0, s[72:73]
	global_load_lds_dwordx4 v[78:79], off
	v_mfma_f32_32x32x16_bf16 v[0:15], v[108:111], v[128:131], v[0:15]
	global_load_lds_dwordx4 v[78:79], off offset:1024
	v_mfma_f32_32x32x16_bf16 v[168:183], v[108:111], v[132:135], v[168:183]
	v_mfma_f32_32x32x16_bf16 v[184:199], v[108:111], v[204:207], v[184:199]
	s_waitcnt vmcnt(6)
	s_waitcnt lgkmcnt(0)
	s_barrier
	ds_read_b128 v[104:107], v116
	ds_read_b128 v[112:115], v119 offset:8192
	v_mfma_f32_32x32x16_bf16 v[48:63], v[208:211], v[244:247], v[48:63]
	ds_read_b128 v[128:131], v119 offset:10240
	ds_read_b128 v[132:135], v119 offset:49152
	v_mfma_f32_32x32x16_bf16 v[32:47], v[208:211], v[250:253], v[32:47]
	ds_read_b128 v[204:207], v119 offset:51200
	ds_read_b128 v[108:111], v116 offset:2048
	v_mfma_f32_32x32x16_bf16 v[136:151], v[208:211], v[68:71], v[136:151]
	v_mfma_f32_32x32x16_bf16 v[152:167], v[208:211], v[74:77], v[152:167]
	ds_read_b128 v[208:211], v122
	v_mfma_f32_32x32x16_bf16 v[16:31], v[214:217], v[244:247], v[16:31]
	ds_read_b128 v[244:247], v125 offset:8192
	v_mfma_f32_32x32x16_bf16 v[0:15], v[214:217], v[250:253], v[0:15]
	ds_read_b128 v[250:253], v125 offset:10240
	v_mfma_f32_32x32x16_bf16 v[168:183], v[214:217], v[68:71], v[168:183]
	ds_read_b128 v[68:71], v125 offset:49152
	v_mfma_f32_32x32x16_bf16 v[184:199], v[214:217], v[74:77], v[184:199]
	ds_read_b128 v[214:217], v122 offset:2048
	ds_read_b128 v[74:77], v125 offset:51200
	s_waitcnt lgkmcnt(6)
	v_mfma_f32_32x32x16_bf16 v[48:63], v[104:107], v[112:115], v[48:63]
	s_mov_b32 m0, s52
	v_lshl_add_u64 v[64:65], v[64:65], 0, s[44:45]
	global_load_lds_dwordx4 v[64:65], off
	v_mfma_f32_32x32x16_bf16 v[32:47], v[104:107], v[128:131], v[32:47]
	global_load_lds_dwordx4 v[64:65], off offset:1024
	v_mfma_f32_32x32x16_bf16 v[136:151], v[104:107], v[132:135], v[136:151]
	s_mov_b32 m0, s55
	v_lshl_add_u64 v[66:67], v[66:67], 0, s[44:45]
	global_load_lds_dwordx4 v[66:67], off
	v_mfma_f32_32x32x16_bf16 v[152:167], v[104:107], v[204:207], v[152:167]
	global_load_lds_dwordx4 v[66:67], off offset:1024
	v_mfma_f32_32x32x16_bf16 v[16:31], v[108:111], v[112:115], v[16:31]
	s_mov_b32 m0, s58
	v_lshl_add_u64 v[78:79], v[66:67], 0, s[72:73]
	global_load_lds_dwordx4 v[78:79], off
	v_mfma_f32_32x32x16_bf16 v[0:15], v[108:111], v[128:131], v[0:15]
	global_load_lds_dwordx4 v[78:79], off offset:1024
	v_mfma_f32_32x32x16_bf16 v[168:183], v[108:111], v[132:135], v[168:183]
	v_mfma_f32_32x32x16_bf16 v[184:199], v[108:111], v[204:207], v[184:199]
	s_waitcnt vmcnt(6)
	s_waitcnt lgkmcnt(0)
	s_barrier
	ds_read_b128 v[104:107], v116 offset:16384
	ds_read_b128 v[112:115], v119 offset:24576
	v_mfma_f32_32x32x16_bf16 v[48:63], v[208:211], v[244:247], v[48:63]
	ds_read_b128 v[128:131], v119 offset:26624
	ds_read_b128 v[132:135], v243 offset:40960
	v_mfma_f32_32x32x16_bf16 v[32:47], v[208:211], v[250:253], v[32:47]
	ds_read_b128 v[204:207], v243 offset:43008
	ds_read_b128 v[108:111], v116 offset:18432
	v_mfma_f32_32x32x16_bf16 v[136:151], v[208:211], v[68:71], v[136:151]
	v_mfma_f32_32x32x16_bf16 v[152:167], v[208:211], v[74:77], v[152:167]
	ds_read_b128 v[208:211], v122 offset:16384
	v_mfma_f32_32x32x16_bf16 v[16:31], v[214:217], v[244:247], v[16:31]
	ds_read_b128 v[244:247], v125 offset:24576
	v_mfma_f32_32x32x16_bf16 v[0:15], v[214:217], v[250:253], v[0:15]
	ds_read_b128 v[250:253], v125 offset:26624
	v_mfma_f32_32x32x16_bf16 v[168:183], v[214:217], v[68:71], v[168:183]
	ds_read_b128 v[68:71], v248 offset:40960
	v_mfma_f32_32x32x16_bf16 v[184:199], v[214:217], v[74:77], v[184:199]
	ds_read_b128 v[214:217], v122 offset:18432
	ds_read_b128 v[74:77], v248 offset:43008
	s_waitcnt lgkmcnt(6)
	v_mfma_f32_32x32x16_bf16 v[48:63], v[104:107], v[112:115], v[48:63]
	s_mov_b32 m0, s50
	v_lshl_add_u64 v[64:65], v[64:65], 0, s[44:45]
	global_load_lds_dwordx4 v[64:65], off
	v_mfma_f32_32x32x16_bf16 v[32:47], v[104:107], v[128:131], v[32:47]
	global_load_lds_dwordx4 v[64:65], off offset:1024
	v_mfma_f32_32x32x16_bf16 v[136:151], v[104:107], v[132:135], v[136:151]
	s_mov_b32 m0, s53
	v_lshl_add_u64 v[66:67], v[66:67], 0, s[44:45]
	global_load_lds_dwordx4 v[66:67], off
	v_mfma_f32_32x32x16_bf16 v[152:167], v[104:107], v[204:207], v[152:167]
	global_load_lds_dwordx4 v[66:67], off offset:1024
	v_mfma_f32_32x32x16_bf16 v[16:31], v[108:111], v[112:115], v[16:31]
	s_mov_b32 m0, s56
	v_lshl_add_u64 v[78:79], v[66:67], 0, s[72:73]
	global_load_lds_dwordx4 v[78:79], off
	v_mfma_f32_32x32x16_bf16 v[0:15], v[108:111], v[128:131], v[0:15]
	global_load_lds_dwordx4 v[78:79], off offset:1024
	v_mfma_f32_32x32x16_bf16 v[168:183], v[108:111], v[132:135], v[168:183]
	v_mfma_f32_32x32x16_bf16 v[184:199], v[108:111], v[204:207], v[184:199]
	s_waitcnt vmcnt(6)
	s_waitcnt lgkmcnt(0)
	s_barrier
	ds_read_b128 v[104:107], v116 offset:32768
	ds_read_b128 v[112:115], v119 offset:40960
	v_mfma_f32_32x32x16_bf16 v[48:63], v[208:211], v[244:247], v[48:63]
	ds_read_b128 v[128:131], v119 offset:43008
	ds_read_b128 v[132:135], v243 offset:57344
	v_mfma_f32_32x32x16_bf16 v[32:47], v[208:211], v[250:253], v[32:47]
	ds_read_b128 v[204:207], v243 offset:59392
	ds_read_b128 v[108:111], v116 offset:34816
	v_mfma_f32_32x32x16_bf16 v[136:151], v[208:211], v[68:71], v[136:151]
	v_mfma_f32_32x32x16_bf16 v[152:167], v[208:211], v[74:77], v[152:167]
	ds_read_b128 v[208:211], v122 offset:32768
	v_mfma_f32_32x32x16_bf16 v[16:31], v[214:217], v[244:247], v[16:31]
	ds_read_b128 v[244:247], v125 offset:40960
	v_mfma_f32_32x32x16_bf16 v[0:15], v[214:217], v[250:253], v[0:15]
	ds_read_b128 v[250:253], v125 offset:43008
	v_mfma_f32_32x32x16_bf16 v[168:183], v[214:217], v[68:71], v[168:183]
	ds_read_b128 v[68:71], v248 offset:57344
	v_mfma_f32_32x32x16_bf16 v[184:199], v[214:217], v[74:77], v[184:199]
	ds_read_b128 v[214:217], v122 offset:34816
	ds_read_b128 v[74:77], v248 offset:59392
	s_waitcnt lgkmcnt(6)
	v_mfma_f32_32x32x16_bf16 v[48:63], v[104:107], v[112:115], v[48:63]
	s_mov_b32 m0, s51
	v_lshl_add_u64 v[64:65], v[64:65], 0, s[44:45]
	global_load_lds_dwordx4 v[64:65], off
	v_mfma_f32_32x32x16_bf16 v[32:47], v[104:107], v[128:131], v[32:47]
	global_load_lds_dwordx4 v[64:65], off offset:1024
	v_mfma_f32_32x32x16_bf16 v[136:151], v[104:107], v[132:135], v[136:151]
	s_mov_b32 m0, s54
	v_lshl_add_u64 v[66:67], v[66:67], 0, s[44:45]
	global_load_lds_dwordx4 v[66:67], off
	v_mfma_f32_32x32x16_bf16 v[152:167], v[104:107], v[204:207], v[152:167]
	global_load_lds_dwordx4 v[66:67], off offset:1024
	v_mfma_f32_32x32x16_bf16 v[16:31], v[108:111], v[112:115], v[16:31]
	s_mov_b32 m0, s57
	v_lshl_add_u64 v[78:79], v[66:67], 0, s[72:73]
	global_load_lds_dwordx4 v[78:79], off
	v_mfma_f32_32x32x16_bf16 v[0:15], v[108:111], v[128:131], v[0:15]
	global_load_lds_dwordx4 v[78:79], off offset:1024
	v_mfma_f32_32x32x16_bf16 v[168:183], v[108:111], v[132:135], v[168:183]
	v_mfma_f32_32x32x16_bf16 v[184:199], v[108:111], v[204:207], v[184:199]
	s_waitcnt vmcnt(6)
	s_waitcnt lgkmcnt(0)
	s_barrier
	ds_read_b128 v[104:107], v116
	ds_read_b128 v[112:115], v119 offset:8192
	v_mfma_f32_32x32x16_bf16 v[48:63], v[208:211], v[244:247], v[48:63]
	ds_read_b128 v[128:131], v119 offset:10240
	ds_read_b128 v[132:135], v119 offset:49152
	v_mfma_f32_32x32x16_bf16 v[32:47], v[208:211], v[250:253], v[32:47]
	ds_read_b128 v[204:207], v119 offset:51200
	ds_read_b128 v[108:111], v116 offset:2048
	v_mfma_f32_32x32x16_bf16 v[136:151], v[208:211], v[68:71], v[136:151]
	v_mfma_f32_32x32x16_bf16 v[152:167], v[208:211], v[74:77], v[152:167]
	ds_read_b128 v[208:211], v122
	v_mfma_f32_32x32x16_bf16 v[16:31], v[214:217], v[244:247], v[16:31]
	ds_read_b128 v[244:247], v125 offset:8192
	v_mfma_f32_32x32x16_bf16 v[0:15], v[214:217], v[250:253], v[0:15]
	ds_read_b128 v[250:253], v125 offset:10240
	v_mfma_f32_32x32x16_bf16 v[168:183], v[214:217], v[68:71], v[168:183]
	ds_read_b128 v[68:71], v125 offset:49152
	v_mfma_f32_32x32x16_bf16 v[184:199], v[214:217], v[74:77], v[184:199]
	ds_read_b128 v[214:217], v122 offset:2048
	ds_read_b128 v[74:77], v125 offset:51200
	s_waitcnt lgkmcnt(6)
	v_mfma_f32_32x32x16_bf16 v[48:63], v[104:107], v[112:115], v[48:63]
	v_mfma_f32_32x32x16_bf16 v[32:47], v[104:107], v[128:131], v[32:47]
	v_mfma_f32_32x32x16_bf16 v[136:151], v[104:107], v[132:135], v[136:151]
	v_mfma_f32_32x32x16_bf16 v[152:167], v[104:107], v[204:207], v[152:167]
	v_mfma_f32_32x32x16_bf16 v[16:31], v[108:111], v[112:115], v[16:31]
	v_mfma_f32_32x32x16_bf16 v[0:15], v[108:111], v[128:131], v[0:15]
	v_mfma_f32_32x32x16_bf16 v[168:183], v[108:111], v[132:135], v[168:183]
	v_mfma_f32_32x32x16_bf16 v[184:199], v[108:111], v[204:207], v[184:199]
	s_waitcnt vmcnt(0)
	s_waitcnt lgkmcnt(0)
	s_barrier
	ds_read_b128 v[104:107], v116 offset:16384
	ds_read_b128 v[112:115], v119 offset:24576
	v_mfma_f32_32x32x16_bf16 v[48:63], v[208:211], v[244:247], v[48:63]
	ds_read_b128 v[128:131], v119 offset:26624
	ds_read_b128 v[132:135], v243 offset:40960
	v_mfma_f32_32x32x16_bf16 v[32:47], v[208:211], v[250:253], v[32:47]
	ds_read_b128 v[204:207], v243 offset:43008
	ds_read_b128 v[108:111], v116 offset:18432
	v_mfma_f32_32x32x16_bf16 v[136:151], v[208:211], v[68:71], v[136:151]
	v_mfma_f32_32x32x16_bf16 v[152:167], v[208:211], v[74:77], v[152:167]
	ds_read_b128 v[208:211], v122 offset:16384
	v_mfma_f32_32x32x16_bf16 v[16:31], v[214:217], v[244:247], v[16:31]
	ds_read_b128 v[244:247], v125 offset:24576
	v_mfma_f32_32x32x16_bf16 v[0:15], v[214:217], v[250:253], v[0:15]
	ds_read_b128 v[250:253], v125 offset:26624
	v_mfma_f32_32x32x16_bf16 v[168:183], v[214:217], v[68:71], v[168:183]
	ds_read_b128 v[68:71], v248 offset:40960
	v_mfma_f32_32x32x16_bf16 v[184:199], v[214:217], v[74:77], v[184:199]
	ds_read_b128 v[214:217], v122 offset:18432
	ds_read_b128 v[74:77], v248 offset:43008
	s_waitcnt lgkmcnt(6)
	v_mfma_f32_32x32x16_bf16 v[48:63], v[104:107], v[112:115], v[48:63]
	v_mfma_f32_32x32x16_bf16 v[32:47], v[104:107], v[128:131], v[32:47]
	v_mfma_f32_32x32x16_bf16 v[136:151], v[104:107], v[132:135], v[136:151]
	v_mfma_f32_32x32x16_bf16 v[152:167], v[104:107], v[204:207], v[152:167]
	v_mfma_f32_32x32x16_bf16 v[16:31], v[108:111], v[112:115], v[16:31]
	v_mfma_f32_32x32x16_bf16 v[0:15], v[108:111], v[128:131], v[0:15]
	v_mfma_f32_32x32x16_bf16 v[168:183], v[108:111], v[132:135], v[168:183]
	v_mfma_f32_32x32x16_bf16 v[184:199], v[108:111], v[204:207], v[184:199]
	s_waitcnt lgkmcnt(0)
	v_mfma_f32_32x32x16_bf16 v[48:63], v[208:211], v[244:247], v[48:63]
	v_mfma_f32_32x32x16_bf16 v[32:47], v[208:211], v[250:253], v[32:47]
	v_mfma_f32_32x32x16_bf16 v[136:151], v[208:211], v[68:71], v[136:151]
	v_mfma_f32_32x32x16_bf16 v[152:167], v[208:211], v[74:77], v[152:167]
	v_mfma_f32_32x32x16_bf16 v[16:31], v[214:217], v[244:247], v[16:31]
	v_mfma_f32_32x32x16_bf16 v[0:15], v[214:217], v[250:253], v[0:15]
	v_mfma_f32_32x32x16_bf16 v[168:183], v[214:217], v[68:71], v[168:183]
	v_mfma_f32_32x32x16_bf16 v[184:199], v[214:217], v[74:77], v[184:199]
	v_add_u32_e32 v79, 0x400, v94
	v_add_u32_e32 v78, 0x2000, v94
	v_add_u32_e32 v77, 0x2400, v94
	v_add_u32_e32 v76, 0x4000, v94
	v_add_u32_e32 v75, 0x4400, v94
	v_add_u32_e32 v74, 0x6000, v94
	v_add_u32_e32 v71, 0x8000, v94
	v_add_u32_e32 v70, 0x8400, v94
	v_add_u32_e32 v69, 0xa000, v94
	v_add_u32_e32 v68, 0xa400, v94
	s_branch .Lgt_post

.Lgt_post:
	s_and_saveexec_b64 s[16:17], s[38:39]
	s_cbranch_execz .LBB0_273
	s_mov_b32 s13, 0x800000
	v_mul_f32_e32 v64, 0x4b800000, v73
	v_cmp_gt_f32_e32 vcc, s13, v73
	s_nop 1
	v_cndmask_b32_e32 v64, v73, v64, vcc
	v_rsq_f32_e32 v64, v64
	s_nop 0
	v_mul_f32_e32 v65, 0x45800000, v64
	v_cndmask_b32_e32 v64, v64, v65, vcc
	ds_write_b32 v101, v64
